# GEMM K-loops (P1,P4,P7,P9,P10): first trip peeled with C=0 MFMAs, 128-v_mov accumulator zero-fill per unit removed
# speedup vs baseline: 1.0251x; 1.0025x over previous
; #define PG8_STAGE(bufoff, gbase, voff) do { _Pragma("unroll") for (int _i = 0; _i < 2; ++_i) \
;         __builtin_amdgcn_global_load_lds((const unsigned*)((const char*)(gbase) + (voff)[_i]), (PG8_LAS unsigned*)(lds + (bufoff) + ldsw + _i * 8192), 16, 0, 0); } while (0)
; #define PG8_LDA(dst, b, h) do { _Pragma("unroll") for (int m = 0; m < 4; ++m) _Pragma("unroll") for (int k = 0; k < 2; ++k) dst[m][k] = *(const PG8_LAS bf16x8*)(lds + PG8_SA(b, h) + aoff + m * 2048 + k * 1024); } while (0)
; #define PG8_LDB(dst, b, h) do { _Pragma("unroll") for (int n = 0; n < 2; ++n) _Pragma("unroll") for (int k = 0; k < 2; ++k) dst[n][k] = *(const PG8_LAS bf16x8*)(lds + PG8_SB(b, h) + boff + n * 2048 + k * 1024); } while (0)
; #define PG8_MMA(ai, bj, At, Bt) do { __builtin_amdgcn_s_setprio(1); _Pragma("unroll") for (int m = 0; m < 4; ++m) _Pragma("unroll") for (int n = 0; n < 2; ++n) _Pragma("unroll") for (int k = 0; k < 2; ++k) \
;         acc[ai][bj][m][n] = __builtin_amdgcn_mfma_f32_16x16x32_bf16(Bt[n][k], At[m][k], acc[ai][bj][m][n], 0, 0, 0); __builtin_amdgcn_s_setprio(0); } while (0)
; #define PG8_BAR __builtin_amdgcn_s_barrier()
; template <class Epi, class Sched, bool ALIGN_EPI = true>
; __device__ __forceinline__ void gemm_phase(PG8_LAS unsigned char* lds, const int K, const Sched& S, const Epi& E) {
;     ...
;         const char* nA = has_next ? S.aptr(nxt) : cA; const char* nB = has_next ? S.bptr(nxt) : cB;
;         unsigned td = 0u;
;         if constexpr (Epi::TOUCH) E.touch(cur, tid, td);
;         for (int t = 0; t < nt; t += 2) {
;             const bool last = (t == nt - 2);
;             const char* a1 = cA + (size_t)(t + 1) * kstep;
;             const char* a2 = last ? nA : cA + (size_t)(t + 2) * kstep; const char* b2 = last ? nB : cB + (size_t)(t + 2) * kstep;
;             const char* a3 = a2 + kstep; const char* b3 = b2 + kstep;
;             PG8_LDB(B0, 0, 0); PG8_LDB(B1, 0, 1); PG8_SCHED; PG8_LDA(At, 0, 0); PG8_STAGE(PG8_SA(1, 1), a1 + hstep, voffA);
;             PG8_WAIT_V(8); PG8_WAIT_L(0); PG8_BAR; PG8_MMA(0, 0, At, B0); PG8_MMA(0, 1, At, B1); PG8_BAR; PG8_SCHED;
;             PG8_LDA(At, 0, 1); PG8_STAGE(PG8_SB(0, 0), b2, voffB); PG8_STAGE(PG8_SB(0, 1), b2 + hstep, voffB); PG8_STAGE(PG8_SA(0, 0), a2, voffA);
;             PG8_WAIT_V(8); PG8_WAIT_L(0); PG8_BAR; PG8_MMA(1, 0, At, B0); PG8_MMA(1, 1, At, B1); PG8_BAR; PG8_SCHED;
.LBB0_177:
	s_cmp_eq_u32 s90, 1
	s_cselect_b32 s76, s7, s36
	s_cselect_b32 s8, s3, s73
	s_cselect_b32 s79, s35, s93
	s_ashr_i32 s77, s76, 31
	s_lshl_b64 s[76:77], s[76:77], 19
	s_add_u32 s76, s8, s76
	s_addc_u32 s77, s79, s77
	s_and_b64 s[4:5], s[4:5], exec
	s_cselect_b32 s8, s77, s83
	s_cselect_b32 s79, s76, s82
	s_add_u32 s4, s84, 0x40080
	s_addc_u32 s5, s85, 0
	s_add_u32 s81, s82, 0x100
	s_addc_u32 s86, s83, 0
	s_mov_b32 s87, -2
	ds_read_b128 v[158:161], v143
	ds_read_b128 v[164:167], v143 offset:1024
	ds_read_b128 v[168:171], v143 offset:2048
	ds_read_b128 v[172:175], v143 offset:3072
	ds_read_b128 v[176:179], v145
	ds_read_b128 v[180:183], v145 offset:1024
	ds_read_b128 v[184:187], v145 offset:2048
	ds_read_b128 v[188:191], v145 offset:3072
	s_add_u32 s82, s4, 0xfffc0080
	s_addc_u32 s83, s5, -1
	s_cmp_eq_u32 s87, 12
	s_cselect_b32 s85, s75, s83
	s_cselect_b32 s84, s74, s82
	s_cselect_b32 s83, s8, s86
	s_cselect_b32 s82, s79, s81
	v_lshl_add_u64 v[224:225], s[4:5], 0, v[150:151]
	s_add_i32 m0, s95, 0xc000
	ds_read_b128 v[192:195], v163
	ds_read_b128 v[196:199], v163 offset:1024
	ds_read_b128 v[200:203], v163 offset:2048
	ds_read_b128 v[204:207], v163 offset:3072
	ds_read_b128 v[208:211], v163 offset:4096
	ds_read_b128 v[212:215], v163 offset:5120
	ds_read_b128 v[216:219], v163 offset:6144
	ds_read_b128 v[220:223], v163 offset:7168
	global_load_lds_dwordx4 v[224:225], off
	s_add_i32 m0, s95, 0xe000
	v_lshl_add_u64 v[224:225], s[4:5], 0, v[152:153]
	global_load_lds_dwordx4 v[224:225], off
	s_waitcnt vmcnt(8)
	s_waitcnt lgkmcnt(0)
	s_barrier
	s_setprio 1
	s_waitcnt lgkmcnt(0)
	v_mfma_f32_16x16x32_bf16 v[126:129], v[158:161], v[192:195], 0
	v_mfma_f32_16x16x32_bf16 v[122:125], v[168:171], v[192:195], 0
	v_mfma_f32_16x16x32_bf16 v[110:113], v[158:161], v[200:203], 0
	v_mfma_f32_16x16x32_bf16 v[106:109], v[168:171], v[200:203], 0
	v_mfma_f32_16x16x32_bf16 v[94:97], v[158:161], v[208:211], 0
	v_mfma_f32_16x16x32_bf16 v[90:93], v[168:171], v[208:211], 0
	v_mfma_f32_16x16x32_bf16 v[78:81], v[158:161], v[216:219], 0
	v_mfma_f32_16x16x32_bf16 v[74:77], v[168:171], v[216:219], 0
	v_mfma_f32_16x16x32_bf16 v[126:129], v[164:167], v[196:199], v[126:129]
	v_mfma_f32_16x16x32_bf16 v[122:125], v[172:175], v[196:199], v[122:125]
	v_mfma_f32_16x16x32_bf16 v[110:113], v[164:167], v[204:207], v[110:113]
	v_mfma_f32_16x16x32_bf16 v[106:109], v[172:175], v[204:207], v[106:109]
	v_mfma_f32_16x16x32_bf16 v[94:97], v[164:167], v[212:215], v[94:97]
	v_mfma_f32_16x16x32_bf16 v[90:93], v[172:175], v[212:215], v[90:93]
	v_mfma_f32_16x16x32_bf16 v[78:81], v[164:167], v[220:223], v[78:81]
	v_mfma_f32_16x16x32_bf16 v[74:77], v[172:175], v[220:223], v[74:77]
	v_mfma_f32_16x16x32_bf16 v[118:121], v[176:179], v[192:195], 0
	v_mfma_f32_16x16x32_bf16 v[114:117], v[184:187], v[192:195], 0
	v_mfma_f32_16x16x32_bf16 v[102:105], v[176:179], v[200:203], 0
	v_mfma_f32_16x16x32_bf16 v[98:101], v[184:187], v[200:203], 0
	v_mfma_f32_16x16x32_bf16 v[86:89], v[176:179], v[208:211], 0
	v_mfma_f32_16x16x32_bf16 v[82:85], v[184:187], v[208:211], 0
	v_mfma_f32_16x16x32_bf16 v[70:73], v[176:179], v[216:219], 0
	v_mfma_f32_16x16x32_bf16 v[66:69], v[184:187], v[216:219], 0
	v_mfma_f32_16x16x32_bf16 v[118:121], v[180:183], v[196:199], v[118:121]
	v_mfma_f32_16x16x32_bf16 v[114:117], v[188:191], v[196:199], v[114:117]
	v_mfma_f32_16x16x32_bf16 v[102:105], v[180:183], v[204:207], v[102:105]
	v_mfma_f32_16x16x32_bf16 v[98:101], v[188:191], v[204:207], v[98:101]
	v_mfma_f32_16x16x32_bf16 v[86:89], v[180:183], v[212:215], v[86:89]
	v_mfma_f32_16x16x32_bf16 v[82:85], v[188:191], v[212:215], v[82:85]
	v_mfma_f32_16x16x32_bf16 v[70:73], v[180:183], v[220:223], v[70:73]
	v_mfma_f32_16x16x32_bf16 v[66:69], v[188:191], v[220:223], v[66:69]
	s_setprio 0
	s_barrier
	s_add_i32 vcc_lo, s44, s94
	v_lshl_add_u64 v[224:225], s[82:83], 0, v[132:133]
	s_mov_b32 m0, vcc_lo
	ds_read_b128 v[192:195], v163 offset:16384
	ds_read_b128 v[196:199], v163 offset:17408
	ds_read_b128 v[200:203], v163 offset:18432
	ds_read_b128 v[204:207], v163 offset:19456
	ds_read_b128 v[208:211], v163 offset:20480
	ds_read_b128 v[212:215], v163 offset:21504
	ds_read_b128 v[216:219], v163 offset:22528
	ds_read_b128 v[220:223], v163 offset:23552
	global_load_lds_dwordx4 v[224:225], off
	s_add_i32 m0, vcc_lo, 0x2000
	s_add_u32 vcc_lo, s82, 0x40000
	v_lshl_add_u64 v[226:227], s[82:83], 0, v[136:137]
	s_addc_u32 vcc_hi, s83, 0
	s_add_i32 s59, s45, s94
	global_load_lds_dwordx4 v[226:227], off
	v_lshl_add_u64 v[228:229], vcc, 0, v[132:133]
	s_mov_b32 m0, s59
	v_lshl_add_u64 v[230:231], s[84:85], 0, v[134:135]
	global_load_lds_dwordx4 v[228:229], off
	s_add_i32 m0, s59, 0x2000
	v_lshl_add_u64 v[228:229], vcc, 0, v[136:137]
	global_load_lds_dwordx4 v[228:229], off
	s_mov_b32 m0, s95
	v_lshl_add_u64 v[228:229], s[84:85], 0, v[130:131]
	global_load_lds_dwordx4 v[228:229], off
	s_mov_b32 m0, s96
	s_nop 0
	global_load_lds_dwordx4 v[230:231], off
	s_waitcnt vmcnt(8)
	s_waitcnt lgkmcnt(0)
	s_barrier
; #define PG8_STAGE(bufoff, gbase, voff) do { _Pragma("unroll") for (int _i = 0; _i < 2; ++_i) \
;         __builtin_amdgcn_global_load_lds((const unsigned*)((const char*)(gbase) + (voff)[_i]), (PG8_LAS unsigned*)(lds + (bufoff) + ldsw + _i * 8192), 16, 0, 0); } while (0)
; #define PG8_LDA(dst, b, h) do { _Pragma("unroll") for (int m = 0; m < 4; ++m) _Pragma("unroll") for (int k = 0; k < 2; ++k) dst[m][k] = *(const PG8_LAS bf16x8*)(lds + PG8_SA(b, h) + aoff + m * 2048 + k * 1024); } while (0)
; #define PG8_LDB(dst, b, h) do { _Pragma("unroll") for (int n = 0; n < 2; ++n) _Pragma("unroll") for (int k = 0; k < 2; ++k) dst[n][k] = *(const PG8_LAS bf16x8*)(lds + PG8_SB(b, h) + boff + n * 2048 + k * 1024); } while (0)
; #define PG8_MMA(ai, bj, At, Bt) do { __builtin_amdgcn_s_setprio(1); _Pragma("unroll") for (int m = 0; m < 4; ++m) _Pragma("unroll") for (int n = 0; n < 2; ++n) _Pragma("unroll") for (int k = 0; k < 2; ++k) \
;         acc[ai][bj][m][n] = __builtin_amdgcn_mfma_f32_16x16x32_bf16(Bt[n][k], At[m][k], acc[ai][bj][m][n], 0, 0, 0); __builtin_amdgcn_s_setprio(0); } while (0)
; #define PG8_WAIT_V(n) asm volatile("s_waitcnt vmcnt(" #n ")" ::: "memory")
; #define PG8_WAIT_L(n) asm volatile("s_waitcnt lgkmcnt(" #n ")" ::: "memory")
; #define PG8_BAR __builtin_amdgcn_s_barrier()
; #define PG8_SCHED __builtin_amdgcn_sched_barrier(0)
; template <class Epi, class Sched, bool ALIGN_EPI = true>
; __device__ __forceinline__ void gemm_phase(PG8_LAS unsigned char* lds, const int K, const Sched& S, const Epi& E) {
;     ...
;             PG8_WAIT_V(8); PG8_WAIT_L(0); PG8_BAR; PG8_MMA(0, 0, At, B0); PG8_MMA(0, 1, At, B1); PG8_BAR; PG8_SCHED;
;             PG8_LDA(At, 0, 1); PG8_STAGE(PG8_SB(0, 0), b2, voffB); PG8_STAGE(PG8_SB(0, 1), b2 + hstep, voffB); PG8_STAGE(PG8_SA(0, 0), a2, voffA);
;             PG8_WAIT_V(8); PG8_WAIT_L(0); PG8_BAR; PG8_MMA(1, 0, At, B0); PG8_MMA(1, 1, At, B1); PG8_BAR; PG8_SCHED;
;             PG8_LDB(B0, 1, 0); PG8_LDB(B1, 1, 1); PG8_SCHED; PG8_LDA(At, 1, 0); PG8_STAGE(PG8_SA(0, 1), a2 + hstep, voffA);
;             PG8_WAIT_V(8); PG8_WAIT_L(0); PG8_BAR; PG8_MMA(0, 0, At, B0); PG8_MMA(0, 1, At, B1); PG8_BAR; PG8_SCHED;
	s_setprio 1
	s_waitcnt lgkmcnt(0)
	v_mfma_f32_16x16x32_bf16 v[62:65], v[158:161], v[192:195], 0
	v_mfma_f32_16x16x32_bf16 v[58:61], v[168:171], v[192:195], 0
	v_mfma_f32_16x16x32_bf16 v[46:49], v[158:161], v[200:203], 0
	v_mfma_f32_16x16x32_bf16 v[42:45], v[168:171], v[200:203], 0
	v_mfma_f32_16x16x32_bf16 v[30:33], v[158:161], v[208:211], 0
	v_mfma_f32_16x16x32_bf16 v[26:29], v[168:171], v[208:211], 0
	v_mfma_f32_16x16x32_bf16 v[14:17], v[158:161], v[216:219], 0
	v_mfma_f32_16x16x32_bf16 v[10:13], v[168:171], v[216:219], 0
	v_mfma_f32_16x16x32_bf16 v[62:65], v[164:167], v[196:199], v[62:65]
	v_mfma_f32_16x16x32_bf16 v[58:61], v[172:175], v[196:199], v[58:61]
	v_mfma_f32_16x16x32_bf16 v[46:49], v[164:167], v[204:207], v[46:49]
	v_mfma_f32_16x16x32_bf16 v[42:45], v[172:175], v[204:207], v[42:45]
	v_mfma_f32_16x16x32_bf16 v[30:33], v[164:167], v[212:215], v[30:33]
	v_mfma_f32_16x16x32_bf16 v[26:29], v[172:175], v[212:215], v[26:29]
	v_mfma_f32_16x16x32_bf16 v[14:17], v[164:167], v[220:223], v[14:17]
	v_mfma_f32_16x16x32_bf16 v[10:13], v[172:175], v[220:223], v[10:13]
	v_mfma_f32_16x16x32_bf16 v[54:57], v[176:179], v[192:195], 0
	v_mfma_f32_16x16x32_bf16 v[50:53], v[184:187], v[192:195], 0
	v_mfma_f32_16x16x32_bf16 v[38:41], v[176:179], v[200:203], 0
	v_mfma_f32_16x16x32_bf16 v[34:37], v[184:187], v[200:203], 0
	v_mfma_f32_16x16x32_bf16 v[22:25], v[176:179], v[208:211], 0
	v_mfma_f32_16x16x32_bf16 v[18:21], v[184:187], v[208:211], 0
	v_mfma_f32_16x16x32_bf16 v[6:9], v[176:179], v[216:219], 0
	v_mfma_f32_16x16x32_bf16 v[2:5], v[184:187], v[216:219], 0
	v_mfma_f32_16x16x32_bf16 v[54:57], v[180:183], v[196:199], v[54:57]
	v_mfma_f32_16x16x32_bf16 v[50:53], v[188:191], v[196:199], v[50:53]
	v_mfma_f32_16x16x32_bf16 v[38:41], v[180:183], v[204:207], v[38:41]
	v_mfma_f32_16x16x32_bf16 v[34:37], v[188:191], v[204:207], v[34:37]
	v_mfma_f32_16x16x32_bf16 v[22:25], v[180:183], v[212:215], v[22:25]
	v_mfma_f32_16x16x32_bf16 v[18:21], v[188:191], v[212:215], v[18:21]
	v_mfma_f32_16x16x32_bf16 v[6:9], v[180:183], v[220:223], v[6:9]
	v_mfma_f32_16x16x32_bf16 v[2:5], v[188:191], v[220:223], v[2:5]
	s_setprio 0
	s_barrier
	s_add_i32 s59, 0, 0x18000
	v_add_u32_e32 v138, s59, v1
	s_add_i32 vcc_lo, 0, 0x1c000
	ds_read_b128 v[158:161], v138
	ds_read_b128 v[164:167], v138 offset:1024
	ds_read_b128 v[168:171], v138 offset:2048
	ds_read_b128 v[172:175], v138 offset:3072
	v_add_u32_e32 v138, vcc_lo, v1
	ds_read_b128 v[176:179], v138
	ds_read_b128 v[180:183], v138 offset:1024
	ds_read_b128 v[184:187], v138 offset:2048
	ds_read_b128 v[188:191], v138 offset:3072
	s_add_u32 s84, s84, 0x40000
	s_addc_u32 s85, s85, 0
	s_mov_b32 m0, s97
	v_lshl_add_u64 v[232:233], s[84:85], 0, v[130:131]
	ds_read_b128 v[192:195], v163 offset:32768
	ds_read_b128 v[196:199], v163 offset:33792
	ds_read_b128 v[200:203], v163 offset:34816
	ds_read_b128 v[204:207], v163 offset:35840
	ds_read_b128 v[208:211], v163 offset:36864
	ds_read_b128 v[212:215], v163 offset:37888
	ds_read_b128 v[216:219], v163 offset:38912
	ds_read_b128 v[220:223], v163 offset:39936
	global_load_lds_dwordx4 v[232:233], off
	s_mov_b32 m0, s58
	v_lshl_add_u64 v[232:233], s[84:85], 0, v[134:135]
	global_load_lds_dwordx4 v[232:233], off
	s_waitcnt vmcnt(8)
	s_waitcnt lgkmcnt(0)
	s_barrier
	s_setprio 1
	s_waitcnt lgkmcnt(0)
	v_mfma_f32_16x16x32_bf16 v[126:129], v[158:161], v[192:195], v[126:129]
	v_mfma_f32_16x16x32_bf16 v[122:125], v[168:171], v[192:195], v[122:125]
	v_mfma_f32_16x16x32_bf16 v[110:113], v[158:161], v[200:203], v[110:113]
	v_mfma_f32_16x16x32_bf16 v[106:109], v[168:171], v[200:203], v[106:109]
	v_mfma_f32_16x16x32_bf16 v[94:97], v[158:161], v[208:211], v[94:97]
	v_mfma_f32_16x16x32_bf16 v[90:93], v[168:171], v[208:211], v[90:93]
	v_mfma_f32_16x16x32_bf16 v[78:81], v[158:161], v[216:219], v[78:81]
	v_mfma_f32_16x16x32_bf16 v[74:77], v[168:171], v[216:219], v[74:77]
	v_mfma_f32_16x16x32_bf16 v[126:129], v[164:167], v[196:199], v[126:129]
	v_mfma_f32_16x16x32_bf16 v[122:125], v[172:175], v[196:199], v[122:125]
	v_mfma_f32_16x16x32_bf16 v[110:113], v[164:167], v[204:207], v[110:113]
	v_mfma_f32_16x16x32_bf16 v[106:109], v[172:175], v[204:207], v[106:109]
	v_mfma_f32_16x16x32_bf16 v[94:97], v[164:167], v[212:215], v[94:97]
	v_mfma_f32_16x16x32_bf16 v[90:93], v[172:175], v[212:215], v[90:93]
	v_mfma_f32_16x16x32_bf16 v[78:81], v[164:167], v[220:223], v[78:81]
	v_mfma_f32_16x16x32_bf16 v[74:77], v[172:175], v[220:223], v[74:77]
	v_mfma_f32_16x16x32_bf16 v[118:121], v[176:179], v[192:195], v[118:121]
	v_mfma_f32_16x16x32_bf16 v[114:117], v[184:187], v[192:195], v[114:117]
	v_mfma_f32_16x16x32_bf16 v[102:105], v[176:179], v[200:203], v[102:105]
	v_mfma_f32_16x16x32_bf16 v[98:101], v[184:187], v[200:203], v[98:101]
	v_mfma_f32_16x16x32_bf16 v[86:89], v[176:179], v[208:211], v[86:89]
	v_mfma_f32_16x16x32_bf16 v[82:85], v[184:187], v[208:211], v[82:85]
	v_mfma_f32_16x16x32_bf16 v[70:73], v[176:179], v[216:219], v[70:73]
	v_mfma_f32_16x16x32_bf16 v[66:69], v[184:187], v[216:219], v[66:69]
	v_mfma_f32_16x16x32_bf16 v[118:121], v[180:183], v[196:199], v[118:121]
	v_mfma_f32_16x16x32_bf16 v[114:117], v[188:191], v[196:199], v[114:117]
	v_mfma_f32_16x16x32_bf16 v[102:105], v[180:183], v[204:207], v[102:105]
	v_mfma_f32_16x16x32_bf16 v[98:101], v[188:191], v[204:207], v[98:101]
	v_mfma_f32_16x16x32_bf16 v[86:89], v[180:183], v[212:215], v[86:89]
	v_mfma_f32_16x16x32_bf16 v[82:85], v[188:191], v[212:215], v[82:85]
	v_mfma_f32_16x16x32_bf16 v[70:73], v[180:183], v[220:223], v[70:73]
	v_mfma_f32_16x16x32_bf16 v[66:69], v[188:191], v[220:223], v[66:69]
	s_setprio 0
	s_barrier
; #define PG8_STAGE(bufoff, gbase, voff) do { _Pragma("unroll") for (int _i = 0; _i < 2; ++_i) \
;         __builtin_amdgcn_global_load_lds((const unsigned*)((const char*)(gbase) + (voff)[_i]), (PG8_LAS unsigned*)(lds + (bufoff) + ldsw + _i * 8192), 16, 0, 0); } while (0)
; #define PG8_LDA(dst, b, h) do { _Pragma("unroll") for (int m = 0; m < 4; ++m) _Pragma("unroll") for (int k = 0; k < 2; ++k) dst[m][k] = *(const PG8_LAS bf16x8*)(lds + PG8_SA(b, h) + aoff + m * 2048 + k * 1024); } while (0)
; #define PG8_MMA(ai, bj, At, Bt) do { __builtin_amdgcn_s_setprio(1); _Pragma("unroll") for (int m = 0; m < 4; ++m) _Pragma("unroll") for (int n = 0; n < 2; ++n) _Pragma("unroll") for (int k = 0; k < 2; ++k) \
;         acc[ai][bj][m][n] = __builtin_amdgcn_mfma_f32_16x16x32_bf16(Bt[n][k], At[m][k], acc[ai][bj][m][n], 0, 0, 0); __builtin_amdgcn_s_setprio(0); } while (0)
; #define PG8_WAIT_V(n) asm volatile("s_waitcnt vmcnt(" #n ")" ::: "memory")
; #define PG8_WAIT_L(n) asm volatile("s_waitcnt lgkmcnt(" #n ")" ::: "memory")
; #define PG8_BAR __builtin_amdgcn_s_barrier()
; #define PG8_SCHED __builtin_amdgcn_sched_barrier(0)
; template <class Epi, class Sched, bool ALIGN_EPI = true>
; __device__ __forceinline__ void gemm_phase(PG8_LAS unsigned char* lds, const int K, const Sched& S, const Epi& E) {
;     ...
;             PG8_LDA(At, 1, 1); PG8_STAGE(PG8_SB(1, 0), b3, voffB); PG8_STAGE(PG8_SB(1, 1), b3 + hstep, voffB); PG8_STAGE(PG8_SA(1, 0), a3, voffA);
;             PG8_WAIT_V(8); PG8_WAIT_L(0); PG8_BAR; PG8_MMA(1, 0, At, B0); PG8_MMA(1, 1, At, B1); PG8_BAR; PG8_SCHED;
;         }
	s_add_i32 s59, s59, s94
	v_lshl_add_u64 v[224:225], v[224:225], 0, s[12:13]
	s_mov_b32 m0, s59
	ds_read_b128 v[192:195], v163 offset:49152
	ds_read_b128 v[196:199], v163 offset:50176
	ds_read_b128 v[200:203], v163 offset:51200
	ds_read_b128 v[204:207], v163 offset:52224
	ds_read_b128 v[208:211], v163 offset:53248
	ds_read_b128 v[212:215], v163 offset:54272
	ds_read_b128 v[216:219], v163 offset:55296
	ds_read_b128 v[220:223], v163 offset:56320
	global_load_lds_dwordx4 v[224:225], off
	s_add_i32 m0, s59, 0x2000
	s_add_u32 s82, s82, 0x40080
	v_lshl_add_u64 v[224:225], v[226:227], 0, s[12:13]
	s_addc_u32 s83, s83, 0
	s_add_i32 s59, vcc_lo, s94
	global_load_lds_dwordx4 v[224:225], off
	s_mov_b32 m0, s59
	v_lshl_add_u64 v[224:225], s[82:83], 0, v[132:133]
	global_load_lds_dwordx4 v[224:225], off
	s_add_i32 m0, s59, 0x2000
	v_lshl_add_u64 v[224:225], s[82:83], 0, v[136:137]
	global_load_lds_dwordx4 v[224:225], off
	s_mov_b32 m0, s91
	v_lshl_add_u64 v[224:225], v[228:229], 0, s[12:13]
	global_load_lds_dwordx4 v[224:225], off
	s_mov_b32 m0, s92
	v_lshl_add_u64 v[224:225], v[230:231], 0, s[12:13]
	global_load_lds_dwordx4 v[224:225], off
	s_waitcnt vmcnt(8)
	s_waitcnt lgkmcnt(0)
	s_barrier
	s_setprio 1
	s_waitcnt lgkmcnt(0)
	v_mfma_f32_16x16x32_bf16 v[62:65], v[158:161], v[192:195], v[62:65]
	v_mfma_f32_16x16x32_bf16 v[58:61], v[168:171], v[192:195], v[58:61]
	v_mfma_f32_16x16x32_bf16 v[46:49], v[158:161], v[200:203], v[46:49]
	v_mfma_f32_16x16x32_bf16 v[42:45], v[168:171], v[200:203], v[42:45]
	v_mfma_f32_16x16x32_bf16 v[30:33], v[158:161], v[208:211], v[30:33]
	v_mfma_f32_16x16x32_bf16 v[26:29], v[168:171], v[208:211], v[26:29]
	v_mfma_f32_16x16x32_bf16 v[14:17], v[158:161], v[216:219], v[14:17]
	v_mfma_f32_16x16x32_bf16 v[10:13], v[168:171], v[216:219], v[10:13]
	v_mfma_f32_16x16x32_bf16 v[62:65], v[164:167], v[196:199], v[62:65]
	v_mfma_f32_16x16x32_bf16 v[58:61], v[172:175], v[196:199], v[58:61]
	v_mfma_f32_16x16x32_bf16 v[46:49], v[164:167], v[204:207], v[46:49]
	v_mfma_f32_16x16x32_bf16 v[42:45], v[172:175], v[204:207], v[42:45]
	v_mfma_f32_16x16x32_bf16 v[30:33], v[164:167], v[212:215], v[30:33]
	v_mfma_f32_16x16x32_bf16 v[26:29], v[172:175], v[212:215], v[26:29]
	v_mfma_f32_16x16x32_bf16 v[14:17], v[164:167], v[220:223], v[14:17]
	v_mfma_f32_16x16x32_bf16 v[10:13], v[172:175], v[220:223], v[10:13]
	v_mfma_f32_16x16x32_bf16 v[54:57], v[176:179], v[192:195], v[54:57]
	v_mfma_f32_16x16x32_bf16 v[50:53], v[184:187], v[192:195], v[50:53]
	v_mfma_f32_16x16x32_bf16 v[38:41], v[176:179], v[200:203], v[38:41]
	v_mfma_f32_16x16x32_bf16 v[34:37], v[184:187], v[200:203], v[34:37]
	v_mfma_f32_16x16x32_bf16 v[22:25], v[176:179], v[208:211], v[22:25]
	v_mfma_f32_16x16x32_bf16 v[18:21], v[184:187], v[208:211], v[18:21]
	v_mfma_f32_16x16x32_bf16 v[6:9], v[176:179], v[216:219], v[6:9]
	v_mfma_f32_16x16x32_bf16 v[2:5], v[184:187], v[216:219], v[2:5]
	v_mfma_f32_16x16x32_bf16 v[54:57], v[180:183], v[196:199], v[54:57]
	v_mfma_f32_16x16x32_bf16 v[50:53], v[188:191], v[196:199], v[50:53]
	v_mfma_f32_16x16x32_bf16 v[38:41], v[180:183], v[204:207], v[38:41]
	v_mfma_f32_16x16x32_bf16 v[34:37], v[188:191], v[204:207], v[34:37]
	v_mfma_f32_16x16x32_bf16 v[22:25], v[180:183], v[212:215], v[22:25]
	v_mfma_f32_16x16x32_bf16 v[18:21], v[188:191], v[212:215], v[18:21]
	v_mfma_f32_16x16x32_bf16 v[6:9], v[180:183], v[220:223], v[6:9]
	v_mfma_f32_16x16x32_bf16 v[2:5], v[188:191], v[220:223], v[2:5]
	s_setprio 0
	s_barrier
	s_add_i32 s87, s87, 2
	s_add_u32 s4, s4, 0x100
	s_addc_u32 s5, s5, 0
	s_add_u32 s81, s81, 0x100
	s_addc_u32 s86, s86, 0
	s_cmp_gt_u32 s87, 13
	s_cbranch_scc0 .LBB0_178
	s_branch .Lkexit_0

; #define PG8_BAR __builtin_amdgcn_s_barrier()
; template <class Epi, class Sched, bool ALIGN_EPI = true>
; __device__ __forceinline__ void gemm_phase(PG8_LAS unsigned char* lds, const int K, const Sched& S, const Epi& E) {
;     ...
;         if constexpr (ALIGN_EPI) { if (wr == 0) PG8_BAR; }
.Lkexit_0:
	s_and_b64 vcc, exec, s[14:15]
	s_cbranch_vccz .LBB0_181
	s_barrier

; #define PG8_STAGE(bufoff, gbase, voff) do { _Pragma("unroll") for (int _i = 0; _i < 2; ++_i) \
;         __builtin_amdgcn_global_load_lds((const unsigned*)((const char*)(gbase) + (voff)[_i]), (PG8_LAS unsigned*)(lds + (bufoff) + ldsw + _i * 8192), 16, 0, 0); } while (0)
; #define PG8_LDA(dst, b, h) do { _Pragma("unroll") for (int m = 0; m < 4; ++m) _Pragma("unroll") for (int k = 0; k < 2; ++k) dst[m][k] = *(const PG8_LAS bf16x8*)(lds + PG8_SA(b, h) + aoff + m * 2048 + k * 1024); } while (0)
; #define PG8_LDB(dst, b, h) do { _Pragma("unroll") for (int n = 0; n < 2; ++n) _Pragma("unroll") for (int k = 0; k < 2; ++k) dst[n][k] = *(const PG8_LAS bf16x8*)(lds + PG8_SB(b, h) + boff + n * 2048 + k * 1024); } while (0)
; #define PG8_MMA(ai, bj, At, Bt) do { __builtin_amdgcn_s_setprio(1); _Pragma("unroll") for (int m = 0; m < 4; ++m) _Pragma("unroll") for (int n = 0; n < 2; ++n) _Pragma("unroll") for (int k = 0; k < 2; ++k) \
;         acc[ai][bj][m][n] = __builtin_amdgcn_mfma_f32_16x16x32_bf16(Bt[n][k], At[m][k], acc[ai][bj][m][n], 0, 0, 0); __builtin_amdgcn_s_setprio(0); } while (0)
; #define PG8_BAR __builtin_amdgcn_s_barrier()
; template <class Epi, class Sched, bool ALIGN_EPI = true>
; __device__ __forceinline__ void gemm_phase(PG8_LAS unsigned char* lds, const int K, const Sched& S, const Epi& E) {
;     ...
;         const char* nA = has_next ? S.aptr(nxt) : cA; const char* nB = has_next ? S.bptr(nxt) : cB;
;         unsigned td = 0u;
;         if constexpr (Epi::TOUCH) E.touch(cur, tid, td);
;         for (int t = 0; t < nt; t += 2) {
;             const bool last = (t == nt - 2);
;             const char* a1 = cA + (size_t)(t + 1) * kstep;
;             const char* a2 = last ? nA : cA + (size_t)(t + 2) * kstep; const char* b2 = last ? nB : cB + (size_t)(t + 2) * kstep;
;             const char* a3 = a2 + kstep; const char* b3 = b2 + kstep;
;             PG8_LDB(B0, 0, 0); PG8_LDB(B1, 0, 1); PG8_SCHED; PG8_LDA(At, 0, 0); PG8_STAGE(PG8_SA(1, 1), a1 + hstep, voffA);
;             PG8_WAIT_V(8); PG8_WAIT_L(0); PG8_BAR; PG8_MMA(0, 0, At, B0); PG8_MMA(0, 1, At, B1); PG8_BAR; PG8_SCHED;
;             PG8_LDA(At, 0, 1); PG8_STAGE(PG8_SB(0, 0), b2, voffB); PG8_STAGE(PG8_SB(0, 1), b2 + hstep, voffB); PG8_STAGE(PG8_SA(0, 0), a2, voffA);
;             PG8_WAIT_V(8); PG8_WAIT_L(0); PG8_BAR; PG8_MMA(1, 0, At, B0); PG8_MMA(1, 1, At, B1); PG8_BAR; PG8_SCHED;
.LBB0_1155:
	s_cmp_eq_u32 s86, 1
	s_cselect_b32 s66, s38, s96
	s_cselect_b32 s16, s35, s78
	s_cselect_b32 s39, s63, s79
	s_ashr_i32 s67, s66, 31
	s_lshl_b64 s[66:67], s[66:67], 19
	s_add_u32 s66, s16, s66
	s_addc_u32 s67, s39, s67
	s_and_b64 s[6:7], s[6:7], exec
	s_cselect_b32 s16, s67, s73
	s_cselect_b32 s39, s66, s72
	s_add_u32 s6, s74, 0x40080
	s_addc_u32 s7, s75, 0
	s_add_u32 s69, s72, 0x100
	s_addc_u32 s71, s73, 0
	s_mov_b32 s76, -2
	ds_read_b128 v[158:161], v143
	ds_read_b128 v[164:167], v143 offset:1024
	ds_read_b128 v[168:171], v143 offset:2048
	ds_read_b128 v[172:175], v143 offset:3072
	ds_read_b128 v[176:179], v145
	ds_read_b128 v[180:183], v145 offset:1024
	ds_read_b128 v[184:187], v145 offset:2048
	ds_read_b128 v[188:191], v145 offset:3072
	s_add_u32 s72, s6, 0xfffc0080
	s_addc_u32 s73, s7, -1
	s_cmp_eq_u32 s76, 12
	s_cselect_b32 s75, s65, s73
	s_cselect_b32 s74, s64, s72
	s_cselect_b32 s73, s16, s71
	s_cselect_b32 s72, s39, s69
	v_lshl_add_u64 v[224:225], s[6:7], 0, v[150:151]
	s_add_i32 m0, s81, 0xc000
	ds_read_b128 v[192:195], v163
	ds_read_b128 v[196:199], v163 offset:1024
	ds_read_b128 v[200:203], v163 offset:2048
	ds_read_b128 v[204:207], v163 offset:3072
	ds_read_b128 v[208:211], v163 offset:4096
	ds_read_b128 v[212:215], v163 offset:5120
	ds_read_b128 v[216:219], v163 offset:6144
	ds_read_b128 v[220:223], v163 offset:7168
	global_load_lds_dwordx4 v[224:225], off
	s_add_i32 m0, s81, 0xe000
	v_lshl_add_u64 v[224:225], s[6:7], 0, v[152:153]
	global_load_lds_dwordx4 v[224:225], off
	s_waitcnt vmcnt(8)
	s_waitcnt lgkmcnt(0)
	s_barrier
	s_setprio 1
	s_waitcnt lgkmcnt(0)
	v_mfma_f32_16x16x32_bf16 v[126:129], v[158:161], v[192:195], 0
	v_mfma_f32_16x16x32_bf16 v[122:125], v[168:171], v[192:195], 0
	v_mfma_f32_16x16x32_bf16 v[110:113], v[158:161], v[200:203], 0
	v_mfma_f32_16x16x32_bf16 v[106:109], v[168:171], v[200:203], 0
	v_mfma_f32_16x16x32_bf16 v[94:97], v[158:161], v[208:211], 0
	v_mfma_f32_16x16x32_bf16 v[90:93], v[168:171], v[208:211], 0
	v_mfma_f32_16x16x32_bf16 v[78:81], v[158:161], v[216:219], 0
	v_mfma_f32_16x16x32_bf16 v[74:77], v[168:171], v[216:219], 0
	v_mfma_f32_16x16x32_bf16 v[126:129], v[164:167], v[196:199], v[126:129]
	v_mfma_f32_16x16x32_bf16 v[122:125], v[172:175], v[196:199], v[122:125]
	v_mfma_f32_16x16x32_bf16 v[110:113], v[164:167], v[204:207], v[110:113]
	v_mfma_f32_16x16x32_bf16 v[106:109], v[172:175], v[204:207], v[106:109]
	v_mfma_f32_16x16x32_bf16 v[94:97], v[164:167], v[212:215], v[94:97]
	v_mfma_f32_16x16x32_bf16 v[90:93], v[172:175], v[212:215], v[90:93]
	v_mfma_f32_16x16x32_bf16 v[78:81], v[164:167], v[220:223], v[78:81]
	v_mfma_f32_16x16x32_bf16 v[74:77], v[172:175], v[220:223], v[74:77]
	v_mfma_f32_16x16x32_bf16 v[118:121], v[176:179], v[192:195], 0
	v_mfma_f32_16x16x32_bf16 v[114:117], v[184:187], v[192:195], 0
	v_mfma_f32_16x16x32_bf16 v[102:105], v[176:179], v[200:203], 0
	v_mfma_f32_16x16x32_bf16 v[98:101], v[184:187], v[200:203], 0
	v_mfma_f32_16x16x32_bf16 v[86:89], v[176:179], v[208:211], 0
	v_mfma_f32_16x16x32_bf16 v[82:85], v[184:187], v[208:211], 0
	v_mfma_f32_16x16x32_bf16 v[70:73], v[176:179], v[216:219], 0
	v_mfma_f32_16x16x32_bf16 v[66:69], v[184:187], v[216:219], 0
	v_mfma_f32_16x16x32_bf16 v[118:121], v[180:183], v[196:199], v[118:121]
	v_mfma_f32_16x16x32_bf16 v[114:117], v[188:191], v[196:199], v[114:117]
	v_mfma_f32_16x16x32_bf16 v[102:105], v[180:183], v[204:207], v[102:105]
	v_mfma_f32_16x16x32_bf16 v[98:101], v[188:191], v[204:207], v[98:101]
	v_mfma_f32_16x16x32_bf16 v[86:89], v[180:183], v[212:215], v[86:89]
	v_mfma_f32_16x16x32_bf16 v[82:85], v[188:191], v[212:215], v[82:85]
	v_mfma_f32_16x16x32_bf16 v[70:73], v[180:183], v[220:223], v[70:73]
	v_mfma_f32_16x16x32_bf16 v[66:69], v[188:191], v[220:223], v[66:69]
	s_setprio 0
	s_barrier
	s_add_i32 s77, s58, s80
	v_lshl_add_u64 v[224:225], s[72:73], 0, v[132:133]
	s_mov_b32 m0, s77
	ds_read_b128 v[192:195], v163 offset:16384
	ds_read_b128 v[196:199], v163 offset:17408
	ds_read_b128 v[200:203], v163 offset:18432
	ds_read_b128 v[204:207], v163 offset:19456
	ds_read_b128 v[208:211], v163 offset:20480
	ds_read_b128 v[212:215], v163 offset:21504
	ds_read_b128 v[216:219], v163 offset:22528
	ds_read_b128 v[220:223], v163 offset:23552
	global_load_lds_dwordx4 v[224:225], off
	s_add_i32 m0, s77, 0x2000
	s_add_u32 vcc_lo, s72, 0x40000
	v_lshl_add_u64 v[226:227], s[72:73], 0, v[136:137]
	s_addc_u32 vcc_hi, s73, 0
	s_add_i32 s77, s59, s80
	global_load_lds_dwordx4 v[226:227], off
	v_lshl_add_u64 v[228:229], vcc, 0, v[132:133]
	s_mov_b32 m0, s77
	v_lshl_add_u64 v[230:231], s[74:75], 0, v[134:135]
	global_load_lds_dwordx4 v[228:229], off
	s_add_i32 m0, s77, 0x2000
	v_lshl_add_u64 v[228:229], vcc, 0, v[136:137]
	global_load_lds_dwordx4 v[228:229], off
	s_mov_b32 m0, s81
	v_lshl_add_u64 v[228:229], s[74:75], 0, v[130:131]
	global_load_lds_dwordx4 v[228:229], off
	s_mov_b32 m0, s82
	s_nop 0
	global_load_lds_dwordx4 v[230:231], off
	s_waitcnt vmcnt(8)
	s_waitcnt lgkmcnt(0)
	s_barrier
; #define PG8_STAGE(bufoff, gbase, voff) do { _Pragma("unroll") for (int _i = 0; _i < 2; ++_i) \
;         __builtin_amdgcn_global_load_lds((const unsigned*)((const char*)(gbase) + (voff)[_i]), (PG8_LAS unsigned*)(lds + (bufoff) + ldsw + _i * 8192), 16, 0, 0); } while (0)
; #define PG8_LDA(dst, b, h) do { _Pragma("unroll") for (int m = 0; m < 4; ++m) _Pragma("unroll") for (int k = 0; k < 2; ++k) dst[m][k] = *(const PG8_LAS bf16x8*)(lds + PG8_SA(b, h) + aoff + m * 2048 + k * 1024); } while (0)
; #define PG8_LDB(dst, b, h) do { _Pragma("unroll") for (int n = 0; n < 2; ++n) _Pragma("unroll") for (int k = 0; k < 2; ++k) dst[n][k] = *(const PG8_LAS bf16x8*)(lds + PG8_SB(b, h) + boff + n * 2048 + k * 1024); } while (0)
; #define PG8_MMA(ai, bj, At, Bt) do { __builtin_amdgcn_s_setprio(1); _Pragma("unroll") for (int m = 0; m < 4; ++m) _Pragma("unroll") for (int n = 0; n < 2; ++n) _Pragma("unroll") for (int k = 0; k < 2; ++k) \
;         acc[ai][bj][m][n] = __builtin_amdgcn_mfma_f32_16x16x32_bf16(Bt[n][k], At[m][k], acc[ai][bj][m][n], 0, 0, 0); __builtin_amdgcn_s_setprio(0); } while (0)
; #define PG8_WAIT_V(n) asm volatile("s_waitcnt vmcnt(" #n ")" ::: "memory")
; #define PG8_WAIT_L(n) asm volatile("s_waitcnt lgkmcnt(" #n ")" ::: "memory")
; #define PG8_BAR __builtin_amdgcn_s_barrier()
; #define PG8_SCHED __builtin_amdgcn_sched_barrier(0)
; template <class Epi, class Sched, bool ALIGN_EPI = true>
; __device__ __forceinline__ void gemm_phase(PG8_LAS unsigned char* lds, const int K, const Sched& S, const Epi& E) {
;     ...
;             PG8_WAIT_V(8); PG8_WAIT_L(0); PG8_BAR; PG8_MMA(0, 0, At, B0); PG8_MMA(0, 1, At, B1); PG8_BAR; PG8_SCHED;
;             PG8_LDA(At, 0, 1); PG8_STAGE(PG8_SB(0, 0), b2, voffB); PG8_STAGE(PG8_SB(0, 1), b2 + hstep, voffB); PG8_STAGE(PG8_SA(0, 0), a2, voffA);
;             PG8_WAIT_V(8); PG8_WAIT_L(0); PG8_BAR; PG8_MMA(1, 0, At, B0); PG8_MMA(1, 1, At, B1); PG8_BAR; PG8_SCHED;
;             PG8_LDB(B0, 1, 0); PG8_LDB(B1, 1, 1); PG8_SCHED; PG8_LDA(At, 1, 0); PG8_STAGE(PG8_SA(0, 1), a2 + hstep, voffA);
;             PG8_WAIT_V(8); PG8_WAIT_L(0); PG8_BAR; PG8_MMA(0, 0, At, B0); PG8_MMA(0, 1, At, B1); PG8_BAR; PG8_SCHED;
	s_setprio 1
	s_waitcnt lgkmcnt(0)
	v_mfma_f32_16x16x32_bf16 v[62:65], v[158:161], v[192:195], 0
	v_mfma_f32_16x16x32_bf16 v[58:61], v[168:171], v[192:195], 0
	v_mfma_f32_16x16x32_bf16 v[46:49], v[158:161], v[200:203], 0
	v_mfma_f32_16x16x32_bf16 v[42:45], v[168:171], v[200:203], 0
	v_mfma_f32_16x16x32_bf16 v[30:33], v[158:161], v[208:211], 0
	v_mfma_f32_16x16x32_bf16 v[26:29], v[168:171], v[208:211], 0
	v_mfma_f32_16x16x32_bf16 v[14:17], v[158:161], v[216:219], 0
	v_mfma_f32_16x16x32_bf16 v[10:13], v[168:171], v[216:219], 0
	v_mfma_f32_16x16x32_bf16 v[62:65], v[164:167], v[196:199], v[62:65]
	v_mfma_f32_16x16x32_bf16 v[58:61], v[172:175], v[196:199], v[58:61]
	v_mfma_f32_16x16x32_bf16 v[46:49], v[164:167], v[204:207], v[46:49]
	v_mfma_f32_16x16x32_bf16 v[42:45], v[172:175], v[204:207], v[42:45]
	v_mfma_f32_16x16x32_bf16 v[30:33], v[164:167], v[212:215], v[30:33]
	v_mfma_f32_16x16x32_bf16 v[26:29], v[172:175], v[212:215], v[26:29]
	v_mfma_f32_16x16x32_bf16 v[14:17], v[164:167], v[220:223], v[14:17]
	v_mfma_f32_16x16x32_bf16 v[10:13], v[172:175], v[220:223], v[10:13]
	v_mfma_f32_16x16x32_bf16 v[54:57], v[176:179], v[192:195], 0
	v_mfma_f32_16x16x32_bf16 v[50:53], v[184:187], v[192:195], 0
	v_mfma_f32_16x16x32_bf16 v[38:41], v[176:179], v[200:203], 0
	v_mfma_f32_16x16x32_bf16 v[34:37], v[184:187], v[200:203], 0
	v_mfma_f32_16x16x32_bf16 v[22:25], v[176:179], v[208:211], 0
	v_mfma_f32_16x16x32_bf16 v[18:21], v[184:187], v[208:211], 0
	v_mfma_f32_16x16x32_bf16 v[6:9], v[176:179], v[216:219], 0
	v_mfma_f32_16x16x32_bf16 v[2:5], v[184:187], v[216:219], 0
	v_mfma_f32_16x16x32_bf16 v[54:57], v[180:183], v[196:199], v[54:57]
	v_mfma_f32_16x16x32_bf16 v[50:53], v[188:191], v[196:199], v[50:53]
	v_mfma_f32_16x16x32_bf16 v[38:41], v[180:183], v[204:207], v[38:41]
	v_mfma_f32_16x16x32_bf16 v[34:37], v[188:191], v[204:207], v[34:37]
	v_mfma_f32_16x16x32_bf16 v[22:25], v[180:183], v[212:215], v[22:25]
	v_mfma_f32_16x16x32_bf16 v[18:21], v[188:191], v[212:215], v[18:21]
	v_mfma_f32_16x16x32_bf16 v[6:9], v[180:183], v[220:223], v[6:9]
	v_mfma_f32_16x16x32_bf16 v[2:5], v[188:191], v[220:223], v[2:5]
	s_setprio 0
	s_barrier
	s_add_i32 s77, 0, 0x18000
	v_add_u32_e32 v138, s77, v1
	s_add_i32 vcc_lo, 0, 0x1c000
	ds_read_b128 v[158:161], v138
	ds_read_b128 v[164:167], v138 offset:1024
	ds_read_b128 v[168:171], v138 offset:2048
	ds_read_b128 v[172:175], v138 offset:3072
	v_add_u32_e32 v138, vcc_lo, v1
	ds_read_b128 v[176:179], v138
	ds_read_b128 v[180:183], v138 offset:1024
	ds_read_b128 v[184:187], v138 offset:2048
	ds_read_b128 v[188:191], v138 offset:3072
	s_add_u32 s74, s74, 0x40000
	s_addc_u32 s75, s75, 0
	s_mov_b32 m0, s83
	v_lshl_add_u64 v[232:233], s[74:75], 0, v[130:131]
	ds_read_b128 v[192:195], v163 offset:32768
	ds_read_b128 v[196:199], v163 offset:33792
	ds_read_b128 v[200:203], v163 offset:34816
	ds_read_b128 v[204:207], v163 offset:35840
	ds_read_b128 v[208:211], v163 offset:36864
	ds_read_b128 v[212:215], v163 offset:37888
	ds_read_b128 v[216:219], v163 offset:38912
	ds_read_b128 v[220:223], v163 offset:39936
	global_load_lds_dwordx4 v[232:233], off
	s_mov_b32 m0, s84
	v_lshl_add_u64 v[232:233], s[74:75], 0, v[134:135]
	global_load_lds_dwordx4 v[232:233], off
	s_waitcnt vmcnt(8)
	s_waitcnt lgkmcnt(0)
	s_barrier
	s_setprio 1
	s_waitcnt lgkmcnt(0)
	v_mfma_f32_16x16x32_bf16 v[126:129], v[158:161], v[192:195], v[126:129]
	v_mfma_f32_16x16x32_bf16 v[122:125], v[168:171], v[192:195], v[122:125]
	v_mfma_f32_16x16x32_bf16 v[110:113], v[158:161], v[200:203], v[110:113]
	v_mfma_f32_16x16x32_bf16 v[106:109], v[168:171], v[200:203], v[106:109]
	v_mfma_f32_16x16x32_bf16 v[94:97], v[158:161], v[208:211], v[94:97]
	v_mfma_f32_16x16x32_bf16 v[90:93], v[168:171], v[208:211], v[90:93]
	v_mfma_f32_16x16x32_bf16 v[78:81], v[158:161], v[216:219], v[78:81]
	v_mfma_f32_16x16x32_bf16 v[74:77], v[168:171], v[216:219], v[74:77]
	v_mfma_f32_16x16x32_bf16 v[126:129], v[164:167], v[196:199], v[126:129]
	v_mfma_f32_16x16x32_bf16 v[122:125], v[172:175], v[196:199], v[122:125]
	v_mfma_f32_16x16x32_bf16 v[110:113], v[164:167], v[204:207], v[110:113]
	v_mfma_f32_16x16x32_bf16 v[106:109], v[172:175], v[204:207], v[106:109]
	v_mfma_f32_16x16x32_bf16 v[94:97], v[164:167], v[212:215], v[94:97]
	v_mfma_f32_16x16x32_bf16 v[90:93], v[172:175], v[212:215], v[90:93]
	v_mfma_f32_16x16x32_bf16 v[78:81], v[164:167], v[220:223], v[78:81]
	v_mfma_f32_16x16x32_bf16 v[74:77], v[172:175], v[220:223], v[74:77]
	v_mfma_f32_16x16x32_bf16 v[118:121], v[176:179], v[192:195], v[118:121]
	v_mfma_f32_16x16x32_bf16 v[114:117], v[184:187], v[192:195], v[114:117]
	v_mfma_f32_16x16x32_bf16 v[102:105], v[176:179], v[200:203], v[102:105]
	v_mfma_f32_16x16x32_bf16 v[98:101], v[184:187], v[200:203], v[98:101]
	v_mfma_f32_16x16x32_bf16 v[86:89], v[176:179], v[208:211], v[86:89]
	v_mfma_f32_16x16x32_bf16 v[82:85], v[184:187], v[208:211], v[82:85]
	v_mfma_f32_16x16x32_bf16 v[70:73], v[176:179], v[216:219], v[70:73]
	v_mfma_f32_16x16x32_bf16 v[66:69], v[184:187], v[216:219], v[66:69]
	v_mfma_f32_16x16x32_bf16 v[118:121], v[180:183], v[196:199], v[118:121]
	v_mfma_f32_16x16x32_bf16 v[114:117], v[188:191], v[196:199], v[114:117]
	v_mfma_f32_16x16x32_bf16 v[102:105], v[180:183], v[204:207], v[102:105]
	v_mfma_f32_16x16x32_bf16 v[98:101], v[188:191], v[204:207], v[98:101]
	v_mfma_f32_16x16x32_bf16 v[86:89], v[180:183], v[212:215], v[86:89]
	v_mfma_f32_16x16x32_bf16 v[82:85], v[188:191], v[212:215], v[82:85]
	v_mfma_f32_16x16x32_bf16 v[70:73], v[180:183], v[220:223], v[70:73]
	v_mfma_f32_16x16x32_bf16 v[66:69], v[188:191], v[220:223], v[66:69]
	s_setprio 0
	s_barrier
; #define PG8_STAGE(bufoff, gbase, voff) do { _Pragma("unroll") for (int _i = 0; _i < 2; ++_i) \
;         __builtin_amdgcn_global_load_lds((const unsigned*)((const char*)(gbase) + (voff)[_i]), (PG8_LAS unsigned*)(lds + (bufoff) + ldsw + _i * 8192), 16, 0, 0); } while (0)
; #define PG8_LDA(dst, b, h) do { _Pragma("unroll") for (int m = 0; m < 4; ++m) _Pragma("unroll") for (int k = 0; k < 2; ++k) dst[m][k] = *(const PG8_LAS bf16x8*)(lds + PG8_SA(b, h) + aoff + m * 2048 + k * 1024); } while (0)
; #define PG8_MMA(ai, bj, At, Bt) do { __builtin_amdgcn_s_setprio(1); _Pragma("unroll") for (int m = 0; m < 4; ++m) _Pragma("unroll") for (int n = 0; n < 2; ++n) _Pragma("unroll") for (int k = 0; k < 2; ++k) \
;         acc[ai][bj][m][n] = __builtin_amdgcn_mfma_f32_16x16x32_bf16(Bt[n][k], At[m][k], acc[ai][bj][m][n], 0, 0, 0); __builtin_amdgcn_s_setprio(0); } while (0)
; #define PG8_WAIT_V(n) asm volatile("s_waitcnt vmcnt(" #n ")" ::: "memory")
; #define PG8_WAIT_L(n) asm volatile("s_waitcnt lgkmcnt(" #n ")" ::: "memory")
; #define PG8_BAR __builtin_amdgcn_s_barrier()
; #define PG8_SCHED __builtin_amdgcn_sched_barrier(0)
; template <class Epi, class Sched, bool ALIGN_EPI = true>
; __device__ __forceinline__ void gemm_phase(PG8_LAS unsigned char* lds, const int K, const Sched& S, const Epi& E) {
;     ...
;             PG8_LDA(At, 1, 1); PG8_STAGE(PG8_SB(1, 0), b3, voffB); PG8_STAGE(PG8_SB(1, 1), b3 + hstep, voffB); PG8_STAGE(PG8_SA(1, 0), a3, voffA);
;             PG8_WAIT_V(8); PG8_WAIT_L(0); PG8_BAR; PG8_MMA(1, 0, At, B0); PG8_MMA(1, 1, At, B1); PG8_BAR; PG8_SCHED;
;         }
	s_add_i32 s74, s77, s80
	v_lshl_add_u64 v[224:225], v[224:225], 0, s[22:23]
	s_mov_b32 m0, s74
	ds_read_b128 v[192:195], v163 offset:49152
	ds_read_b128 v[196:199], v163 offset:50176
	ds_read_b128 v[200:203], v163 offset:51200
	ds_read_b128 v[204:207], v163 offset:52224
	ds_read_b128 v[208:211], v163 offset:53248
	ds_read_b128 v[212:215], v163 offset:54272
	ds_read_b128 v[216:219], v163 offset:55296
	ds_read_b128 v[220:223], v163 offset:56320
	global_load_lds_dwordx4 v[224:225], off
	s_add_i32 m0, s74, 0x2000
	s_add_u32 s72, s72, 0x40080
	v_lshl_add_u64 v[224:225], v[226:227], 0, s[22:23]
	s_addc_u32 s73, s73, 0
	s_add_i32 s74, vcc_lo, s80
	global_load_lds_dwordx4 v[224:225], off
	s_mov_b32 m0, s74
	v_lshl_add_u64 v[224:225], s[72:73], 0, v[132:133]
	global_load_lds_dwordx4 v[224:225], off
	s_add_i32 m0, s74, 0x2000
	v_lshl_add_u64 v[224:225], s[72:73], 0, v[136:137]
	global_load_lds_dwordx4 v[224:225], off
	s_mov_b32 m0, s92
	v_lshl_add_u64 v[224:225], v[228:229], 0, s[22:23]
	global_load_lds_dwordx4 v[224:225], off
	s_mov_b32 m0, s93
	v_lshl_add_u64 v[224:225], v[230:231], 0, s[22:23]
	global_load_lds_dwordx4 v[224:225], off
	s_waitcnt vmcnt(8)
	s_waitcnt lgkmcnt(0)
	s_barrier
	s_setprio 1
	s_waitcnt lgkmcnt(0)
	v_mfma_f32_16x16x32_bf16 v[62:65], v[158:161], v[192:195], v[62:65]
	v_mfma_f32_16x16x32_bf16 v[58:61], v[168:171], v[192:195], v[58:61]
	v_mfma_f32_16x16x32_bf16 v[46:49], v[158:161], v[200:203], v[46:49]
	v_mfma_f32_16x16x32_bf16 v[42:45], v[168:171], v[200:203], v[42:45]
	v_mfma_f32_16x16x32_bf16 v[30:33], v[158:161], v[208:211], v[30:33]
	v_mfma_f32_16x16x32_bf16 v[26:29], v[168:171], v[208:211], v[26:29]
	v_mfma_f32_16x16x32_bf16 v[14:17], v[158:161], v[216:219], v[14:17]
	v_mfma_f32_16x16x32_bf16 v[10:13], v[168:171], v[216:219], v[10:13]
	v_mfma_f32_16x16x32_bf16 v[62:65], v[164:167], v[196:199], v[62:65]
	v_mfma_f32_16x16x32_bf16 v[58:61], v[172:175], v[196:199], v[58:61]
	v_mfma_f32_16x16x32_bf16 v[46:49], v[164:167], v[204:207], v[46:49]
	v_mfma_f32_16x16x32_bf16 v[42:45], v[172:175], v[204:207], v[42:45]
	v_mfma_f32_16x16x32_bf16 v[30:33], v[164:167], v[212:215], v[30:33]
	v_mfma_f32_16x16x32_bf16 v[26:29], v[172:175], v[212:215], v[26:29]
	v_mfma_f32_16x16x32_bf16 v[14:17], v[164:167], v[220:223], v[14:17]
	v_mfma_f32_16x16x32_bf16 v[10:13], v[172:175], v[220:223], v[10:13]
	v_mfma_f32_16x16x32_bf16 v[54:57], v[176:179], v[192:195], v[54:57]
	v_mfma_f32_16x16x32_bf16 v[50:53], v[184:187], v[192:195], v[50:53]
	v_mfma_f32_16x16x32_bf16 v[38:41], v[176:179], v[200:203], v[38:41]
	v_mfma_f32_16x16x32_bf16 v[34:37], v[184:187], v[200:203], v[34:37]
	v_mfma_f32_16x16x32_bf16 v[22:25], v[176:179], v[208:211], v[22:25]
	v_mfma_f32_16x16x32_bf16 v[18:21], v[184:187], v[208:211], v[18:21]
	v_mfma_f32_16x16x32_bf16 v[6:9], v[176:179], v[216:219], v[6:9]
	v_mfma_f32_16x16x32_bf16 v[2:5], v[184:187], v[216:219], v[2:5]
	v_mfma_f32_16x16x32_bf16 v[54:57], v[180:183], v[196:199], v[54:57]
	v_mfma_f32_16x16x32_bf16 v[50:53], v[188:191], v[196:199], v[50:53]
	v_mfma_f32_16x16x32_bf16 v[38:41], v[180:183], v[204:207], v[38:41]
	v_mfma_f32_16x16x32_bf16 v[34:37], v[188:191], v[204:207], v[34:37]
	v_mfma_f32_16x16x32_bf16 v[22:25], v[180:183], v[212:215], v[22:25]
	v_mfma_f32_16x16x32_bf16 v[18:21], v[188:191], v[212:215], v[18:21]
	v_mfma_f32_16x16x32_bf16 v[6:9], v[180:183], v[220:223], v[6:9]
	v_mfma_f32_16x16x32_bf16 v[2:5], v[188:191], v[220:223], v[2:5]
	s_setprio 0
	s_barrier
	s_add_i32 s76, s76, 2
	s_add_u32 s6, s6, 0x100
	s_addc_u32 s7, s7, 0
	s_add_u32 s69, s69, 0x100
	s_addc_u32 s71, s71, 0
	s_cmp_gt_u32 s76, 13
	s_cbranch_scc0 .LBB0_1156
	s_branch .Lkexit_1

; #define PG8_BAR __builtin_amdgcn_s_barrier()
; template <class Epi, class Sched, bool ALIGN_EPI = true>
; __device__ __forceinline__ void gemm_phase(PG8_LAS unsigned char* lds, const int K, const Sched& S, const Epi& E) {
;     ...
;         if constexpr (ALIGN_EPI) { if (wr == 0) PG8_BAR; }
.Lkexit_1:
	s_and_b64 vcc, exec, s[24:25]
	s_cbranch_vccz .LBB0_1159
	s_barrier

; #define PG8_STAGE(bufoff, gbase, voff) do { _Pragma("unroll") for (int _i = 0; _i < 2; ++_i) \
;         __builtin_amdgcn_global_load_lds((const unsigned*)((const char*)(gbase) + (voff)[_i]), (PG8_LAS unsigned*)(lds + (bufoff) + ldsw + _i * 8192), 16, 0, 0); } while (0)
; #define PG8_LDA(dst, b, h) do { _Pragma("unroll") for (int m = 0; m < 4; ++m) _Pragma("unroll") for (int k = 0; k < 2; ++k) dst[m][k] = *(const PG8_LAS bf16x8*)(lds + PG8_SA(b, h) + aoff + m * 2048 + k * 1024); } while (0)
; #define PG8_LDB(dst, b, h) do { _Pragma("unroll") for (int n = 0; n < 2; ++n) _Pragma("unroll") for (int k = 0; k < 2; ++k) dst[n][k] = *(const PG8_LAS bf16x8*)(lds + PG8_SB(b, h) + boff + n * 2048 + k * 1024); } while (0)
; #define PG8_MMA(ai, bj, At, Bt) do { __builtin_amdgcn_s_setprio(1); _Pragma("unroll") for (int m = 0; m < 4; ++m) _Pragma("unroll") for (int n = 0; n < 2; ++n) _Pragma("unroll") for (int k = 0; k < 2; ++k) \
;         acc[ai][bj][m][n] = __builtin_amdgcn_mfma_f32_16x16x32_bf16(Bt[n][k], At[m][k], acc[ai][bj][m][n], 0, 0, 0); __builtin_amdgcn_s_setprio(0); } while (0)
; #define PG8_BAR __builtin_amdgcn_s_barrier()
; template <class Epi, class Sched, bool ALIGN_EPI = true>
; __device__ __forceinline__ void gemm_phase(PG8_LAS unsigned char* lds, const int K, const Sched& S, const Epi& E) {
;     ...
;         const char* nA = has_next ? S.aptr(nxt) : cA; const char* nB = has_next ? S.bptr(nxt) : cB;
;         unsigned td = 0u;
;         if constexpr (Epi::TOUCH) E.touch(cur, tid, td);
;         for (int t = 0; t < nt; t += 2) {
;             const bool last = (t == nt - 2);
;             const char* a1 = cA + (size_t)(t + 1) * kstep;
;             const char* a2 = last ? nA : cA + (size_t)(t + 2) * kstep; const char* b2 = last ? nB : cB + (size_t)(t + 2) * kstep;
;             const char* a3 = a2 + kstep; const char* b3 = b2 + kstep;
;             PG8_LDB(B0, 0, 0); PG8_LDB(B1, 0, 1); PG8_SCHED; PG8_LDA(At, 0, 0); PG8_STAGE(PG8_SA(1, 1), a1 + hstep, voffA);
;             PG8_WAIT_V(8); PG8_WAIT_L(0); PG8_BAR; PG8_MMA(0, 0, At, B0); PG8_MMA(0, 1, At, B1); PG8_BAR; PG8_SCHED;
;             PG8_LDA(At, 0, 1); PG8_STAGE(PG8_SB(0, 0), b2, voffB); PG8_STAGE(PG8_SB(0, 1), b2 + hstep, voffB); PG8_STAGE(PG8_SA(0, 0), a2, voffA);
;             PG8_WAIT_V(8); PG8_WAIT_L(0); PG8_BAR; PG8_MMA(1, 0, At, B0); PG8_MMA(1, 1, At, B1); PG8_BAR; PG8_SCHED;
.LBB0_1597:
	s_ashr_i32 s65, s64, 31
	s_lshl_b64 s[66:67], s[64:65], 19
	s_add_u32 s66, s3, s66
	s_addc_u32 s67, s33, s67
	s_and_b64 s[68:69], s[10:11], exec
	s_cselect_b32 s13, s67, s73
	s_cselect_b32 s65, s66, s72
	s_ashr_i32 s63, s62, 31
	s_lshl_b64 s[68:69], s[62:63], 19
	s_add_u32 s68, s35, s68
	s_addc_u32 s69, s41, s69
	s_and_b64 s[76:77], s[10:11], exec
	s_cselect_b32 s63, s69, s75
	s_cselect_b32 s71, s68, s74
	s_add_u32 s72, s72, 0x40080
	s_addc_u32 s73, s73, 0
	s_add_u32 s91, s74, 0x100
	s_addc_u32 s92, s75, 0
	s_mov_b32 s93, -2
	ds_read_b128 v[130:133], v181
	ds_read_b128 v[134:137], v181 offset:1024
	ds_read_b128 v[138:141], v181 offset:2048
	ds_read_b128 v[142:145], v181 offset:3072
	ds_read_b128 v[146:149], v182
	ds_read_b128 v[168:171], v182 offset:1024
	ds_read_b128 v[172:175], v182 offset:2048
	ds_read_b128 v[192:195], v182 offset:3072
	s_add_u32 s74, s72, 0xfffc0080
	s_addc_u32 s75, s73, -1
	s_cmp_eq_u32 s93, 12
	s_cselect_b32 s77, s13, s75
	s_cselect_b32 s76, s65, s74
	s_cselect_b32 s75, s63, s92
	s_cselect_b32 s74, s71, s91
	v_lshl_add_u64 v[176:177], s[72:73], 0, v[156:157]
	s_add_i32 m0, s57, 0xc000
	ds_read_b128 v[196:199], v183
	ds_read_b128 v[200:203], v183 offset:1024
	ds_read_b128 v[204:207], v183 offset:2048
	ds_read_b128 v[208:211], v183 offset:3072
	ds_read_b128 v[212:215], v183 offset:4096
	ds_read_b128 v[216:219], v183 offset:5120
	ds_read_b128 v[220:223], v183 offset:6144
	ds_read_b128 v[224:227], v183 offset:7168
	global_load_lds_dwordx4 v[176:177], off
	s_add_i32 m0, s57, 0xe000
	v_lshl_add_u64 v[176:177], s[72:73], 0, v[158:159]
	global_load_lds_dwordx4 v[176:177], off
	s_waitcnt vmcnt(8)
	s_waitcnt lgkmcnt(0)
	s_barrier
	s_setprio 1
	s_waitcnt lgkmcnt(0)
	v_mfma_f32_16x16x32_bf16 v[26:29], v[130:133], v[196:199], 0
	v_mfma_f32_16x16x32_bf16 v[14:17], v[138:141], v[196:199], 0
	v_mfma_f32_16x16x32_bf16 v[42:45], v[130:133], v[204:207], 0
	v_mfma_f32_16x16x32_bf16 v[30:33], v[138:141], v[204:207], 0
	v_mfma_f32_16x16x32_bf16 v[74:77], v[130:133], v[212:215], 0
	v_mfma_f32_16x16x32_bf16 v[46:49], v[138:141], v[212:215], 0
	v_mfma_f32_16x16x32_bf16 v[90:93], v[130:133], v[220:223], 0
	v_mfma_f32_16x16x32_bf16 v[78:81], v[138:141], v[220:223], 0
	v_mfma_f32_16x16x32_bf16 v[26:29], v[134:137], v[200:203], v[26:29]
	v_mfma_f32_16x16x32_bf16 v[14:17], v[142:145], v[200:203], v[14:17]
	v_mfma_f32_16x16x32_bf16 v[42:45], v[134:137], v[208:211], v[42:45]
	v_mfma_f32_16x16x32_bf16 v[30:33], v[142:145], v[208:211], v[30:33]
	v_mfma_f32_16x16x32_bf16 v[74:77], v[134:137], v[216:219], v[74:77]
	v_mfma_f32_16x16x32_bf16 v[46:49], v[142:145], v[216:219], v[46:49]
	v_mfma_f32_16x16x32_bf16 v[90:93], v[134:137], v[224:227], v[90:93]
	v_mfma_f32_16x16x32_bf16 v[78:81], v[142:145], v[224:227], v[78:81]
	v_mfma_f32_16x16x32_bf16 v[6:9], v[146:149], v[196:199], 0
	v_mfma_f32_16x16x32_bf16 v[2:5], v[172:175], v[196:199], 0
	v_mfma_f32_16x16x32_bf16 v[18:21], v[146:149], v[204:207], 0
	v_mfma_f32_16x16x32_bf16 v[10:13], v[172:175], v[204:207], 0
	v_mfma_f32_16x16x32_bf16 v[34:37], v[146:149], v[212:215], 0
	v_mfma_f32_16x16x32_bf16 v[22:25], v[172:175], v[212:215], 0
	v_mfma_f32_16x16x32_bf16 v[50:53], v[146:149], v[220:223], 0
	v_mfma_f32_16x16x32_bf16 v[38:41], v[172:175], v[220:223], 0
	v_mfma_f32_16x16x32_bf16 v[6:9], v[168:171], v[200:203], v[6:9]
	v_mfma_f32_16x16x32_bf16 v[2:5], v[192:195], v[200:203], v[2:5]
	v_mfma_f32_16x16x32_bf16 v[18:21], v[168:171], v[208:211], v[18:21]
	v_mfma_f32_16x16x32_bf16 v[10:13], v[192:195], v[208:211], v[10:13]
	v_mfma_f32_16x16x32_bf16 v[34:37], v[168:171], v[216:219], v[34:37]
	v_mfma_f32_16x16x32_bf16 v[22:25], v[192:195], v[216:219], v[22:25]
	v_mfma_f32_16x16x32_bf16 v[50:53], v[168:171], v[224:227], v[50:53]
	v_mfma_f32_16x16x32_bf16 v[38:41], v[192:195], v[224:227], v[38:41]
	s_setprio 0
	s_barrier
	s_add_i32 s94, s86, s56
	v_lshl_add_u64 v[176:177], s[74:75], 0, v[150:151]
	s_mov_b32 m0, s94
	ds_read_b128 v[196:199], v183 offset:16384
	ds_read_b128 v[200:203], v183 offset:17408
	ds_read_b128 v[204:207], v183 offset:18432
	ds_read_b128 v[208:211], v183 offset:19456
	ds_read_b128 v[212:215], v183 offset:20480
	ds_read_b128 v[216:219], v183 offset:21504
	ds_read_b128 v[220:223], v183 offset:22528
	ds_read_b128 v[224:227], v183 offset:23552
	global_load_lds_dwordx4 v[176:177], off
	s_add_i32 m0, s94, 0x2000
	s_add_u32 s94, s74, 0x40000
	v_lshl_add_u64 v[228:229], s[74:75], 0, v[152:153]
	s_addc_u32 s95, s75, 0
	s_add_i32 s96, s87, s56
	global_load_lds_dwordx4 v[228:229], off
	v_lshl_add_u64 v[230:231], s[94:95], 0, v[150:151]
	s_mov_b32 m0, s96
	v_lshl_add_u64 v[232:233], s[76:77], 0, v[152:153]
	global_load_lds_dwordx4 v[230:231], off
	s_add_i32 m0, s96, 0x2000
	v_lshl_add_u64 v[230:231], s[94:95], 0, v[152:153]
	global_load_lds_dwordx4 v[230:231], off
	s_mov_b32 m0, s57
	v_lshl_add_u64 v[230:231], s[76:77], 0, v[150:151]
	global_load_lds_dwordx4 v[230:231], off
	s_mov_b32 m0, s58
	s_nop 0
	global_load_lds_dwordx4 v[232:233], off
	s_waitcnt vmcnt(8)
	s_waitcnt lgkmcnt(0)
	s_barrier
; #define PG8_STAGE(bufoff, gbase, voff) do { _Pragma("unroll") for (int _i = 0; _i < 2; ++_i) \
;         __builtin_amdgcn_global_load_lds((const unsigned*)((const char*)(gbase) + (voff)[_i]), (PG8_LAS unsigned*)(lds + (bufoff) + ldsw + _i * 8192), 16, 0, 0); } while (0)
; #define PG8_LDA(dst, b, h) do { _Pragma("unroll") for (int m = 0; m < 4; ++m) _Pragma("unroll") for (int k = 0; k < 2; ++k) dst[m][k] = *(const PG8_LAS bf16x8*)(lds + PG8_SA(b, h) + aoff + m * 2048 + k * 1024); } while (0)
; #define PG8_LDB(dst, b, h) do { _Pragma("unroll") for (int n = 0; n < 2; ++n) _Pragma("unroll") for (int k = 0; k < 2; ++k) dst[n][k] = *(const PG8_LAS bf16x8*)(lds + PG8_SB(b, h) + boff + n * 2048 + k * 1024); } while (0)
; #define PG8_MMA(ai, bj, At, Bt) do { __builtin_amdgcn_s_setprio(1); _Pragma("unroll") for (int m = 0; m < 4; ++m) _Pragma("unroll") for (int n = 0; n < 2; ++n) _Pragma("unroll") for (int k = 0; k < 2; ++k) \
;         acc[ai][bj][m][n] = __builtin_amdgcn_mfma_f32_16x16x32_bf16(Bt[n][k], At[m][k], acc[ai][bj][m][n], 0, 0, 0); __builtin_amdgcn_s_setprio(0); } while (0)
; #define PG8_WAIT_V(n) asm volatile("s_waitcnt vmcnt(" #n ")" ::: "memory")
; #define PG8_WAIT_L(n) asm volatile("s_waitcnt lgkmcnt(" #n ")" ::: "memory")
; #define PG8_BAR __builtin_amdgcn_s_barrier()
; #define PG8_SCHED __builtin_amdgcn_sched_barrier(0)
; template <class Epi, class Sched, bool ALIGN_EPI = true>
; __device__ __forceinline__ void gemm_phase(PG8_LAS unsigned char* lds, const int K, const Sched& S, const Epi& E) {
;     ...
;             PG8_WAIT_V(8); PG8_WAIT_L(0); PG8_BAR; PG8_MMA(0, 0, At, B0); PG8_MMA(0, 1, At, B1); PG8_BAR; PG8_SCHED;
;             PG8_LDA(At, 0, 1); PG8_STAGE(PG8_SB(0, 0), b2, voffB); PG8_STAGE(PG8_SB(0, 1), b2 + hstep, voffB); PG8_STAGE(PG8_SA(0, 0), a2, voffA);
;             PG8_WAIT_V(8); PG8_WAIT_L(0); PG8_BAR; PG8_MMA(1, 0, At, B0); PG8_MMA(1, 1, At, B1); PG8_BAR; PG8_SCHED;
;             PG8_LDB(B0, 1, 0); PG8_LDB(B1, 1, 1); PG8_SCHED; PG8_LDA(At, 1, 0); PG8_STAGE(PG8_SA(0, 1), a2 + hstep, voffA);
;             PG8_WAIT_V(8); PG8_WAIT_L(0); PG8_BAR; PG8_MMA(0, 0, At, B0); PG8_MMA(0, 1, At, B1); PG8_BAR; PG8_SCHED;
	s_setprio 1
	s_waitcnt lgkmcnt(0)
	v_mfma_f32_16x16x32_bf16 v[122:125], v[130:133], v[196:199], 0
	v_mfma_f32_16x16x32_bf16 v[94:97], v[138:141], v[196:199], 0
	v_mfma_f32_16x16x32_bf16 v[126:129], v[130:133], v[204:207], 0
	v_mfma_f32_16x16x32_bf16 v[118:121], v[138:141], v[204:207], 0
	v_mfma_f32_16x16x32_bf16 v[114:117], v[130:133], v[212:215], 0
	v_mfma_f32_16x16x32_bf16 v[110:113], v[138:141], v[212:215], 0
	v_mfma_f32_16x16x32_bf16 v[70:73], v[130:133], v[220:223], 0
	v_mfma_f32_16x16x32_bf16 v[66:69], v[138:141], v[220:223], 0
	v_mfma_f32_16x16x32_bf16 v[122:125], v[134:137], v[200:203], v[122:125]
	v_mfma_f32_16x16x32_bf16 v[94:97], v[142:145], v[200:203], v[94:97]
	v_mfma_f32_16x16x32_bf16 v[126:129], v[134:137], v[208:211], v[126:129]
	v_mfma_f32_16x16x32_bf16 v[118:121], v[142:145], v[208:211], v[118:121]
	v_mfma_f32_16x16x32_bf16 v[114:117], v[134:137], v[216:219], v[114:117]
	v_mfma_f32_16x16x32_bf16 v[110:113], v[142:145], v[216:219], v[110:113]
	v_mfma_f32_16x16x32_bf16 v[70:73], v[134:137], v[224:227], v[70:73]
	v_mfma_f32_16x16x32_bf16 v[66:69], v[142:145], v[224:227], v[66:69]
	v_mfma_f32_16x16x32_bf16 v[82:85], v[146:149], v[196:199], 0
	v_mfma_f32_16x16x32_bf16 v[54:57], v[172:175], v[196:199], 0
	v_mfma_f32_16x16x32_bf16 v[102:105], v[146:149], v[204:207], 0
	v_mfma_f32_16x16x32_bf16 v[86:89], v[172:175], v[204:207], 0
	v_mfma_f32_16x16x32_bf16 v[106:109], v[146:149], v[212:215], 0
	v_mfma_f32_16x16x32_bf16 v[98:101], v[172:175], v[212:215], 0
	v_mfma_f32_16x16x32_bf16 v[62:65], v[146:149], v[220:223], 0
	v_mfma_f32_16x16x32_bf16 v[58:61], v[172:175], v[220:223], 0
	v_mfma_f32_16x16x32_bf16 v[82:85], v[168:171], v[200:203], v[82:85]
	v_mfma_f32_16x16x32_bf16 v[54:57], v[192:195], v[200:203], v[54:57]
	v_mfma_f32_16x16x32_bf16 v[102:105], v[168:171], v[208:211], v[102:105]
	v_mfma_f32_16x16x32_bf16 v[86:89], v[192:195], v[208:211], v[86:89]
	v_mfma_f32_16x16x32_bf16 v[106:109], v[168:171], v[216:219], v[106:109]
	v_mfma_f32_16x16x32_bf16 v[98:101], v[192:195], v[216:219], v[98:101]
	v_mfma_f32_16x16x32_bf16 v[62:65], v[168:171], v[224:227], v[62:65]
	v_mfma_f32_16x16x32_bf16 v[58:61], v[192:195], v[224:227], v[58:61]
	s_setprio 0
	s_barrier
	s_add_i32 s94, 0, 0x18000
	s_add_i32 s95, 0, 0x1c000
	v_add_u32_e32 v142, s94, v1
	v_add_u32_e32 v191, s95, v1
	ds_read_b128 v[130:133], v142
	ds_read_b128 v[134:137], v142 offset:1024
	ds_read_b128 v[138:141], v142 offset:2048
	ds_read_b128 v[142:145], v142 offset:3072
	ds_read_b128 v[146:149], v191
	ds_read_b128 v[168:171], v191 offset:1024
	ds_read_b128 v[172:175], v191 offset:2048
	ds_read_b128 v[192:195], v191 offset:3072
	s_add_u32 s76, s76, 0x40000
	s_addc_u32 s77, s77, 0
	s_mov_b32 m0, s59
	v_lshl_add_u64 v[234:235], s[76:77], 0, v[150:151]
	ds_read_b128 v[196:199], v183 offset:32768
	ds_read_b128 v[200:203], v183 offset:33792
	ds_read_b128 v[204:207], v183 offset:34816
	ds_read_b128 v[208:211], v183 offset:35840
	ds_read_b128 v[212:215], v183 offset:36864
	ds_read_b128 v[216:219], v183 offset:37888
	ds_read_b128 v[220:223], v183 offset:38912
	ds_read_b128 v[224:227], v183 offset:39936
	global_load_lds_dwordx4 v[234:235], off
	s_mov_b32 m0, s78
	v_lshl_add_u64 v[234:235], s[76:77], 0, v[152:153]
	global_load_lds_dwordx4 v[234:235], off
	s_waitcnt vmcnt(8)
	s_waitcnt lgkmcnt(0)
	s_barrier
	s_setprio 1
	s_waitcnt lgkmcnt(0)
	v_mfma_f32_16x16x32_bf16 v[26:29], v[130:133], v[196:199], v[26:29]
	v_mfma_f32_16x16x32_bf16 v[14:17], v[138:141], v[196:199], v[14:17]
	v_mfma_f32_16x16x32_bf16 v[42:45], v[130:133], v[204:207], v[42:45]
	v_mfma_f32_16x16x32_bf16 v[30:33], v[138:141], v[204:207], v[30:33]
	v_mfma_f32_16x16x32_bf16 v[74:77], v[130:133], v[212:215], v[74:77]
	v_mfma_f32_16x16x32_bf16 v[46:49], v[138:141], v[212:215], v[46:49]
	v_mfma_f32_16x16x32_bf16 v[90:93], v[130:133], v[220:223], v[90:93]
	v_mfma_f32_16x16x32_bf16 v[78:81], v[138:141], v[220:223], v[78:81]
	v_mfma_f32_16x16x32_bf16 v[26:29], v[134:137], v[200:203], v[26:29]
	v_mfma_f32_16x16x32_bf16 v[14:17], v[142:145], v[200:203], v[14:17]
	v_mfma_f32_16x16x32_bf16 v[42:45], v[134:137], v[208:211], v[42:45]
	v_mfma_f32_16x16x32_bf16 v[30:33], v[142:145], v[208:211], v[30:33]
	v_mfma_f32_16x16x32_bf16 v[74:77], v[134:137], v[216:219], v[74:77]
	v_mfma_f32_16x16x32_bf16 v[46:49], v[142:145], v[216:219], v[46:49]
	v_mfma_f32_16x16x32_bf16 v[90:93], v[134:137], v[224:227], v[90:93]
	v_mfma_f32_16x16x32_bf16 v[78:81], v[142:145], v[224:227], v[78:81]
	v_mfma_f32_16x16x32_bf16 v[6:9], v[146:149], v[196:199], v[6:9]
	v_mfma_f32_16x16x32_bf16 v[2:5], v[172:175], v[196:199], v[2:5]
	v_mfma_f32_16x16x32_bf16 v[18:21], v[146:149], v[204:207], v[18:21]
	v_mfma_f32_16x16x32_bf16 v[10:13], v[172:175], v[204:207], v[10:13]
	v_mfma_f32_16x16x32_bf16 v[34:37], v[146:149], v[212:215], v[34:37]
	v_mfma_f32_16x16x32_bf16 v[22:25], v[172:175], v[212:215], v[22:25]
	v_mfma_f32_16x16x32_bf16 v[50:53], v[146:149], v[220:223], v[50:53]
	v_mfma_f32_16x16x32_bf16 v[38:41], v[172:175], v[220:223], v[38:41]
	v_mfma_f32_16x16x32_bf16 v[6:9], v[168:171], v[200:203], v[6:9]
	v_mfma_f32_16x16x32_bf16 v[2:5], v[192:195], v[200:203], v[2:5]
	v_mfma_f32_16x16x32_bf16 v[18:21], v[168:171], v[208:211], v[18:21]
	v_mfma_f32_16x16x32_bf16 v[10:13], v[192:195], v[208:211], v[10:13]
	v_mfma_f32_16x16x32_bf16 v[34:37], v[168:171], v[216:219], v[34:37]
	v_mfma_f32_16x16x32_bf16 v[22:25], v[192:195], v[216:219], v[22:25]
	v_mfma_f32_16x16x32_bf16 v[50:53], v[168:171], v[224:227], v[50:53]
	v_mfma_f32_16x16x32_bf16 v[38:41], v[192:195], v[224:227], v[38:41]
	s_setprio 0
	s_barrier
; #define PG8_STAGE(bufoff, gbase, voff) do { _Pragma("unroll") for (int _i = 0; _i < 2; ++_i) \
;         __builtin_amdgcn_global_load_lds((const unsigned*)((const char*)(gbase) + (voff)[_i]), (PG8_LAS unsigned*)(lds + (bufoff) + ldsw + _i * 8192), 16, 0, 0); } while (0)
; #define PG8_LDA(dst, b, h) do { _Pragma("unroll") for (int m = 0; m < 4; ++m) _Pragma("unroll") for (int k = 0; k < 2; ++k) dst[m][k] = *(const PG8_LAS bf16x8*)(lds + PG8_SA(b, h) + aoff + m * 2048 + k * 1024); } while (0)
; #define PG8_MMA(ai, bj, At, Bt) do { __builtin_amdgcn_s_setprio(1); _Pragma("unroll") for (int m = 0; m < 4; ++m) _Pragma("unroll") for (int n = 0; n < 2; ++n) _Pragma("unroll") for (int k = 0; k < 2; ++k) \
;         acc[ai][bj][m][n] = __builtin_amdgcn_mfma_f32_16x16x32_bf16(Bt[n][k], At[m][k], acc[ai][bj][m][n], 0, 0, 0); __builtin_amdgcn_s_setprio(0); } while (0)
; #define PG8_WAIT_V(n) asm volatile("s_waitcnt vmcnt(" #n ")" ::: "memory")
; #define PG8_WAIT_L(n) asm volatile("s_waitcnt lgkmcnt(" #n ")" ::: "memory")
; #define PG8_BAR __builtin_amdgcn_s_barrier()
; #define PG8_SCHED __builtin_amdgcn_sched_barrier(0)
; template <class Epi, class Sched, bool ALIGN_EPI = true>
; __device__ __forceinline__ void gemm_phase(PG8_LAS unsigned char* lds, const int K, const Sched& S, const Epi& E) {
;     ...
;             PG8_LDA(At, 1, 1); PG8_STAGE(PG8_SB(1, 0), b3, voffB); PG8_STAGE(PG8_SB(1, 1), b3 + hstep, voffB); PG8_STAGE(PG8_SA(1, 0), a3, voffA);
;             PG8_WAIT_V(8); PG8_WAIT_L(0); PG8_BAR; PG8_MMA(1, 0, At, B0); PG8_MMA(1, 1, At, B1); PG8_BAR; PG8_SCHED;
;         }
	s_add_i32 s76, s94, s56
	v_lshl_add_u64 v[176:177], v[176:177], 0, s[24:25]
	s_mov_b32 m0, s76
	ds_read_b128 v[196:199], v183 offset:49152
	ds_read_b128 v[200:203], v183 offset:50176
	ds_read_b128 v[204:207], v183 offset:51200
	ds_read_b128 v[208:211], v183 offset:52224
	ds_read_b128 v[212:215], v183 offset:53248
	ds_read_b128 v[216:219], v183 offset:54272
	ds_read_b128 v[220:223], v183 offset:55296
	ds_read_b128 v[224:227], v183 offset:56320
	global_load_lds_dwordx4 v[176:177], off
	s_add_i32 m0, s76, 0x2000
	s_add_u32 s74, s74, 0x40080
	v_lshl_add_u64 v[176:177], v[228:229], 0, s[24:25]
	s_addc_u32 s75, s75, 0
	s_add_i32 s76, s95, s56
	global_load_lds_dwordx4 v[176:177], off
	s_mov_b32 m0, s76
	v_lshl_add_u64 v[176:177], s[74:75], 0, v[150:151]
	global_load_lds_dwordx4 v[176:177], off
	s_add_i32 m0, s76, 0x2000
	v_lshl_add_u64 v[176:177], s[74:75], 0, v[152:153]
	global_load_lds_dwordx4 v[176:177], off
	s_mov_b32 m0, s82
	v_lshl_add_u64 v[176:177], v[230:231], 0, s[24:25]
	global_load_lds_dwordx4 v[176:177], off
	s_mov_b32 m0, s83
	v_lshl_add_u64 v[176:177], v[232:233], 0, s[24:25]
	global_load_lds_dwordx4 v[176:177], off
	s_waitcnt vmcnt(8)
	s_waitcnt lgkmcnt(0)
	s_barrier
	s_setprio 1
	s_waitcnt lgkmcnt(0)
	v_mfma_f32_16x16x32_bf16 v[122:125], v[130:133], v[196:199], v[122:125]
	v_mfma_f32_16x16x32_bf16 v[94:97], v[138:141], v[196:199], v[94:97]
	v_mfma_f32_16x16x32_bf16 v[126:129], v[130:133], v[204:207], v[126:129]
	v_mfma_f32_16x16x32_bf16 v[118:121], v[138:141], v[204:207], v[118:121]
	v_mfma_f32_16x16x32_bf16 v[114:117], v[130:133], v[212:215], v[114:117]
	v_mfma_f32_16x16x32_bf16 v[110:113], v[138:141], v[212:215], v[110:113]
	v_mfma_f32_16x16x32_bf16 v[70:73], v[130:133], v[220:223], v[70:73]
	v_mfma_f32_16x16x32_bf16 v[66:69], v[138:141], v[220:223], v[66:69]
	v_mfma_f32_16x16x32_bf16 v[122:125], v[134:137], v[200:203], v[122:125]
	v_mfma_f32_16x16x32_bf16 v[94:97], v[142:145], v[200:203], v[94:97]
	v_mfma_f32_16x16x32_bf16 v[126:129], v[134:137], v[208:211], v[126:129]
	v_mfma_f32_16x16x32_bf16 v[118:121], v[142:145], v[208:211], v[118:121]
	v_mfma_f32_16x16x32_bf16 v[114:117], v[134:137], v[216:219], v[114:117]
	v_mfma_f32_16x16x32_bf16 v[110:113], v[142:145], v[216:219], v[110:113]
	v_mfma_f32_16x16x32_bf16 v[70:73], v[134:137], v[224:227], v[70:73]
	v_mfma_f32_16x16x32_bf16 v[66:69], v[142:145], v[224:227], v[66:69]
	v_mfma_f32_16x16x32_bf16 v[82:85], v[146:149], v[196:199], v[82:85]
	v_mfma_f32_16x16x32_bf16 v[54:57], v[172:175], v[196:199], v[54:57]
	v_mfma_f32_16x16x32_bf16 v[102:105], v[146:149], v[204:207], v[102:105]
	v_mfma_f32_16x16x32_bf16 v[86:89], v[172:175], v[204:207], v[86:89]
	v_mfma_f32_16x16x32_bf16 v[106:109], v[146:149], v[212:215], v[106:109]
	v_mfma_f32_16x16x32_bf16 v[98:101], v[172:175], v[212:215], v[98:101]
	v_mfma_f32_16x16x32_bf16 v[62:65], v[146:149], v[220:223], v[62:65]
	v_mfma_f32_16x16x32_bf16 v[58:61], v[172:175], v[220:223], v[58:61]
	v_mfma_f32_16x16x32_bf16 v[82:85], v[168:171], v[200:203], v[82:85]
	v_mfma_f32_16x16x32_bf16 v[54:57], v[192:195], v[200:203], v[54:57]
	v_mfma_f32_16x16x32_bf16 v[102:105], v[168:171], v[208:211], v[102:105]
	v_mfma_f32_16x16x32_bf16 v[86:89], v[192:195], v[208:211], v[86:89]
	v_mfma_f32_16x16x32_bf16 v[106:109], v[168:171], v[216:219], v[106:109]
	v_mfma_f32_16x16x32_bf16 v[98:101], v[192:195], v[216:219], v[98:101]
	v_mfma_f32_16x16x32_bf16 v[62:65], v[168:171], v[224:227], v[62:65]
	v_mfma_f32_16x16x32_bf16 v[58:61], v[192:195], v[224:227], v[58:61]
	s_setprio 0
	s_barrier
	s_add_i32 s93, s93, 2
	s_add_u32 s72, s72, 0x100
	s_addc_u32 s73, s73, 0
	s_add_u32 s91, s91, 0x100
	s_addc_u32 s92, s92, 0
	s_cmp_gt_u32 s93, 13
	s_cbranch_scc0 .LBB0_1598
	s_branch .Lkexit_2

; #define PG8_BAR __builtin_amdgcn_s_barrier()
; template <class Epi, class Sched, bool ALIGN_EPI = true>
; __device__ __forceinline__ void gemm_phase(PG8_LAS unsigned char* lds, const int K, const Sched& S, const Epi& E) {
;     ...
;         if constexpr (ALIGN_EPI) { if (wr == 0) PG8_BAR; }
.Lkexit_2:
	s_and_b64 vcc, exec, s[36:37]
	s_cbranch_vccz .LBB0_1601
	s_barrier

; #define PG8_STAGE(bufoff, gbase, voff) do { _Pragma("unroll") for (int _i = 0; _i < 2; ++_i) \
;         __builtin_amdgcn_global_load_lds((const unsigned*)((const char*)(gbase) + (voff)[_i]), (PG8_LAS unsigned*)(lds + (bufoff) + ldsw + _i * 8192), 16, 0, 0); } while (0)
; #define PG8_LDA(dst, b, h) do { _Pragma("unroll") for (int m = 0; m < 4; ++m) _Pragma("unroll") for (int k = 0; k < 2; ++k) dst[m][k] = *(const PG8_LAS bf16x8*)(lds + PG8_SA(b, h) + aoff + m * 2048 + k * 1024); } while (0)
; #define PG8_LDB(dst, b, h) do { _Pragma("unroll") for (int n = 0; n < 2; ++n) _Pragma("unroll") for (int k = 0; k < 2; ++k) dst[n][k] = *(const PG8_LAS bf16x8*)(lds + PG8_SB(b, h) + boff + n * 2048 + k * 1024); } while (0)
; #define PG8_MMA(ai, bj, At, Bt) do { __builtin_amdgcn_s_setprio(1); _Pragma("unroll") for (int m = 0; m < 4; ++m) _Pragma("unroll") for (int n = 0; n < 2; ++n) _Pragma("unroll") for (int k = 0; k < 2; ++k) \
;         acc[ai][bj][m][n] = __builtin_amdgcn_mfma_f32_16x16x32_bf16(Bt[n][k], At[m][k], acc[ai][bj][m][n], 0, 0, 0); __builtin_amdgcn_s_setprio(0); } while (0)
; #define PG8_BAR __builtin_amdgcn_s_barrier()
; template <class Epi, class Sched, bool ALIGN_EPI = true>
; __device__ __forceinline__ void gemm_phase(PG8_LAS unsigned char* lds, const int K, const Sched& S, const Epi& E) {
;     ...
;         const char* nA = has_next ? S.aptr(nxt) : cA; const char* nB = has_next ? S.bptr(nxt) : cB;
;         unsigned td = 0u;
;         if constexpr (Epi::TOUCH) E.touch(cur, tid, td);
;         for (int t = 0; t < nt; t += 2) {
;             const bool last = (t == nt - 2);
;             const char* a1 = cA + (size_t)(t + 1) * kstep;
;             const char* a2 = last ? nA : cA + (size_t)(t + 2) * kstep; const char* b2 = last ? nB : cB + (size_t)(t + 2) * kstep;
;             const char* a3 = a2 + kstep; const char* b3 = b2 + kstep;
;             PG8_LDB(B0, 0, 0); PG8_LDB(B1, 0, 1); PG8_SCHED; PG8_LDA(At, 0, 0); PG8_STAGE(PG8_SA(1, 1), a1 + hstep, voffA);
;             PG8_WAIT_V(8); PG8_WAIT_L(0); PG8_BAR; PG8_MMA(0, 0, At, B0); PG8_MMA(0, 1, At, B1); PG8_BAR; PG8_SCHED;
;             PG8_LDA(At, 0, 1); PG8_STAGE(PG8_SB(0, 0), b2, voffB); PG8_STAGE(PG8_SB(0, 1), b2 + hstep, voffB); PG8_STAGE(PG8_SA(0, 0), a2, voffA);
;             PG8_WAIT_V(8); PG8_WAIT_L(0); PG8_BAR; PG8_MMA(1, 0, At, B0); PG8_MMA(1, 1, At, B1); PG8_BAR; PG8_SCHED;
.LBB0_1712:
	s_ashr_i32 s17, s16, 31
	s_lshl_b64 s[18:19], s[16:17], 19
	s_add_u32 s18, s33, s18
	s_addc_u32 s19, s35, s19
	s_and_b64 s[20:21], s[0:1], exec
	s_cselect_b32 s17, s19, s37
	s_cselect_b32 s23, s18, s36
	s_ashr_i32 s15, s14, 31
	s_lshl_b64 s[20:21], s[14:15], 19
	s_add_u32 s20, s42, s20
	s_addc_u32 s21, s43, s21
	s_and_b64 s[40:41], s[0:1], exec
	s_cselect_b32 s15, s21, s39
	s_cselect_b32 s25, s20, s38
	s_add_u32 s36, s36, 0x40080
	s_addc_u32 s37, s37, 0
	s_add_u32 s66, s38, 0x100
	s_addc_u32 s67, s39, 0
	s_mov_b32 s68, -2
	ds_read_b128 v[156:159], v152
	ds_read_b128 v[164:167], v152 offset:1024
	ds_read_b128 v[168:171], v152 offset:2048
	ds_read_b128 v[172:175], v152 offset:3072
	ds_read_b128 v[176:179], v153
	ds_read_b128 v[180:183], v153 offset:1024
	ds_read_b128 v[184:187], v153 offset:2048
	ds_read_b128 v[188:191], v153 offset:3072
	s_add_u32 s38, s36, 0xfffc0080
	s_addc_u32 s39, s37, -1
	s_cmp_eq_u32 s68, 12
	s_cselect_b32 s41, s17, s39
	s_cselect_b32 s40, s23, s38
	s_cselect_b32 s39, s15, s67
	s_cselect_b32 s38, s25, s66
	v_lshl_add_u64 v[150:151], s[36:37], 0, v[142:143]
	s_add_i32 m0, s45, 0xc000
	ds_read_b128 v[192:195], v154
	ds_read_b128 v[196:199], v154 offset:1024
	ds_read_b128 v[200:203], v154 offset:2048
	ds_read_b128 v[204:207], v154 offset:3072
	ds_read_b128 v[208:211], v154 offset:4096
	ds_read_b128 v[212:215], v154 offset:5120
	ds_read_b128 v[216:219], v154 offset:6144
	ds_read_b128 v[220:223], v154 offset:7168
	global_load_lds_dwordx4 v[150:151], off
	s_add_i32 m0, s45, 0xe000
	v_lshl_add_u64 v[150:151], s[36:37], 0, v[144:145]
	global_load_lds_dwordx4 v[150:151], off
	s_waitcnt vmcnt(8)
	s_waitcnt lgkmcnt(0)
	s_barrier
	s_setprio 1
	s_waitcnt lgkmcnt(0)
	v_mfma_f32_16x16x32_bf16 v[126:129], v[156:159], v[192:195], 0
	v_mfma_f32_16x16x32_bf16 v[122:125], v[168:171], v[192:195], 0
	v_mfma_f32_16x16x32_bf16 v[114:117], v[156:159], v[200:203], 0
	v_mfma_f32_16x16x32_bf16 v[106:109], v[168:171], v[200:203], 0
	v_mfma_f32_16x16x32_bf16 v[98:101], v[156:159], v[208:211], 0
	v_mfma_f32_16x16x32_bf16 v[90:93], v[168:171], v[208:211], 0
	v_mfma_f32_16x16x32_bf16 v[82:85], v[156:159], v[216:219], 0
	v_mfma_f32_16x16x32_bf16 v[74:77], v[168:171], v[216:219], 0
	v_mfma_f32_16x16x32_bf16 v[126:129], v[164:167], v[196:199], v[126:129]
	v_mfma_f32_16x16x32_bf16 v[122:125], v[172:175], v[196:199], v[122:125]
	v_mfma_f32_16x16x32_bf16 v[114:117], v[164:167], v[204:207], v[114:117]
	v_mfma_f32_16x16x32_bf16 v[106:109], v[172:175], v[204:207], v[106:109]
	v_mfma_f32_16x16x32_bf16 v[98:101], v[164:167], v[212:215], v[98:101]
	v_mfma_f32_16x16x32_bf16 v[90:93], v[172:175], v[212:215], v[90:93]
	v_mfma_f32_16x16x32_bf16 v[82:85], v[164:167], v[220:223], v[82:85]
	v_mfma_f32_16x16x32_bf16 v[74:77], v[172:175], v[220:223], v[74:77]
	v_mfma_f32_16x16x32_bf16 v[118:121], v[176:179], v[192:195], 0
	v_mfma_f32_16x16x32_bf16 v[110:113], v[184:187], v[192:195], 0
	v_mfma_f32_16x16x32_bf16 v[102:105], v[176:179], v[200:203], 0
	v_mfma_f32_16x16x32_bf16 v[94:97], v[184:187], v[200:203], 0
	v_mfma_f32_16x16x32_bf16 v[86:89], v[176:179], v[208:211], 0
	v_mfma_f32_16x16x32_bf16 v[78:81], v[184:187], v[208:211], 0
	v_mfma_f32_16x16x32_bf16 v[70:73], v[176:179], v[216:219], 0
	v_mfma_f32_16x16x32_bf16 v[66:69], v[184:187], v[216:219], 0
	v_mfma_f32_16x16x32_bf16 v[118:121], v[180:183], v[196:199], v[118:121]
	v_mfma_f32_16x16x32_bf16 v[110:113], v[188:191], v[196:199], v[110:113]
	v_mfma_f32_16x16x32_bf16 v[102:105], v[180:183], v[204:207], v[102:105]
	v_mfma_f32_16x16x32_bf16 v[94:97], v[188:191], v[204:207], v[94:97]
	v_mfma_f32_16x16x32_bf16 v[86:89], v[180:183], v[212:215], v[86:89]
	v_mfma_f32_16x16x32_bf16 v[78:81], v[188:191], v[212:215], v[78:81]
	v_mfma_f32_16x16x32_bf16 v[70:73], v[180:183], v[220:223], v[70:73]
	v_mfma_f32_16x16x32_bf16 v[66:69], v[188:191], v[220:223], v[66:69]
	s_setprio 0
	s_barrier
	s_add_i32 s69, s56, s44
	v_lshl_add_u64 v[150:151], s[38:39], 0, v[132:133]
	s_mov_b32 m0, s69
	ds_read_b128 v[192:195], v154 offset:16384
	ds_read_b128 v[196:199], v154 offset:17408
	ds_read_b128 v[200:203], v154 offset:18432
	ds_read_b128 v[204:207], v154 offset:19456
	ds_read_b128 v[208:211], v154 offset:20480
	ds_read_b128 v[212:215], v154 offset:21504
	ds_read_b128 v[216:219], v154 offset:22528
	ds_read_b128 v[220:223], v154 offset:23552
	global_load_lds_dwordx4 v[150:151], off
	s_add_i32 m0, s69, 0x2000
	s_add_u32 s70, s38, 0x40000
	v_lshl_add_u64 v[160:161], s[38:39], 0, v[136:137]
	s_addc_u32 s71, s39, 0
	s_add_i32 s69, s57, s44
	global_load_lds_dwordx4 v[160:161], off
	v_lshl_add_u64 v[224:225], s[70:71], 0, v[132:133]
	s_mov_b32 m0, s69
	v_lshl_add_u64 v[226:227], s[40:41], 0, v[134:135]
	global_load_lds_dwordx4 v[224:225], off
	s_add_i32 m0, s69, 0x2000
	v_lshl_add_u64 v[224:225], s[70:71], 0, v[136:137]
	global_load_lds_dwordx4 v[224:225], off
	s_mov_b32 m0, s45
	v_lshl_add_u64 v[224:225], s[40:41], 0, v[130:131]
	global_load_lds_dwordx4 v[224:225], off
	s_mov_b32 m0, s46
	s_nop 0
	global_load_lds_dwordx4 v[226:227], off
	s_waitcnt vmcnt(8)
	s_waitcnt lgkmcnt(0)
	s_barrier
; #define PG8_STAGE(bufoff, gbase, voff) do { _Pragma("unroll") for (int _i = 0; _i < 2; ++_i) \
;         __builtin_amdgcn_global_load_lds((const unsigned*)((const char*)(gbase) + (voff)[_i]), (PG8_LAS unsigned*)(lds + (bufoff) + ldsw + _i * 8192), 16, 0, 0); } while (0)
; #define PG8_LDA(dst, b, h) do { _Pragma("unroll") for (int m = 0; m < 4; ++m) _Pragma("unroll") for (int k = 0; k < 2; ++k) dst[m][k] = *(const PG8_LAS bf16x8*)(lds + PG8_SA(b, h) + aoff + m * 2048 + k * 1024); } while (0)
; #define PG8_LDB(dst, b, h) do { _Pragma("unroll") for (int n = 0; n < 2; ++n) _Pragma("unroll") for (int k = 0; k < 2; ++k) dst[n][k] = *(const PG8_LAS bf16x8*)(lds + PG8_SB(b, h) + boff + n * 2048 + k * 1024); } while (0)
; #define PG8_MMA(ai, bj, At, Bt) do { __builtin_amdgcn_s_setprio(1); _Pragma("unroll") for (int m = 0; m < 4; ++m) _Pragma("unroll") for (int n = 0; n < 2; ++n) _Pragma("unroll") for (int k = 0; k < 2; ++k) \
;         acc[ai][bj][m][n] = __builtin_amdgcn_mfma_f32_16x16x32_bf16(Bt[n][k], At[m][k], acc[ai][bj][m][n], 0, 0, 0); __builtin_amdgcn_s_setprio(0); } while (0)
; #define PG8_WAIT_V(n) asm volatile("s_waitcnt vmcnt(" #n ")" ::: "memory")
; #define PG8_WAIT_L(n) asm volatile("s_waitcnt lgkmcnt(" #n ")" ::: "memory")
; #define PG8_BAR __builtin_amdgcn_s_barrier()
; #define PG8_SCHED __builtin_amdgcn_sched_barrier(0)
; template <class Epi, class Sched, bool ALIGN_EPI = true>
; __device__ __forceinline__ void gemm_phase(PG8_LAS unsigned char* lds, const int K, const Sched& S, const Epi& E) {
;     ...
;             PG8_WAIT_V(8); PG8_WAIT_L(0); PG8_BAR; PG8_MMA(0, 0, At, B0); PG8_MMA(0, 1, At, B1); PG8_BAR; PG8_SCHED;
;             PG8_LDA(At, 0, 1); PG8_STAGE(PG8_SB(0, 0), b2, voffB); PG8_STAGE(PG8_SB(0, 1), b2 + hstep, voffB); PG8_STAGE(PG8_SA(0, 0), a2, voffA);
;             PG8_WAIT_V(8); PG8_WAIT_L(0); PG8_BAR; PG8_MMA(1, 0, At, B0); PG8_MMA(1, 1, At, B1); PG8_BAR; PG8_SCHED;
;             PG8_LDB(B0, 1, 0); PG8_LDB(B1, 1, 1); PG8_SCHED; PG8_LDA(At, 1, 0); PG8_STAGE(PG8_SA(0, 1), a2 + hstep, voffA);
;             PG8_WAIT_V(8); PG8_WAIT_L(0); PG8_BAR; PG8_MMA(0, 0, At, B0); PG8_MMA(0, 1, At, B1); PG8_BAR; PG8_SCHED;
	s_setprio 1
	s_waitcnt lgkmcnt(0)
	v_mfma_f32_16x16x32_bf16 v[62:65], v[156:159], v[192:195], 0
	v_mfma_f32_16x16x32_bf16 v[58:61], v[168:171], v[192:195], 0
	v_mfma_f32_16x16x32_bf16 v[50:53], v[156:159], v[200:203], 0
	v_mfma_f32_16x16x32_bf16 v[42:45], v[168:171], v[200:203], 0
	v_mfma_f32_16x16x32_bf16 v[34:37], v[156:159], v[208:211], 0
	v_mfma_f32_16x16x32_bf16 v[26:29], v[168:171], v[208:211], 0
	v_mfma_f32_16x16x32_bf16 v[18:21], v[156:159], v[216:219], 0
	v_mfma_f32_16x16x32_bf16 v[10:13], v[168:171], v[216:219], 0
	v_mfma_f32_16x16x32_bf16 v[62:65], v[164:167], v[196:199], v[62:65]
	v_mfma_f32_16x16x32_bf16 v[58:61], v[172:175], v[196:199], v[58:61]
	v_mfma_f32_16x16x32_bf16 v[50:53], v[164:167], v[204:207], v[50:53]
	v_mfma_f32_16x16x32_bf16 v[42:45], v[172:175], v[204:207], v[42:45]
	v_mfma_f32_16x16x32_bf16 v[34:37], v[164:167], v[212:215], v[34:37]
	v_mfma_f32_16x16x32_bf16 v[26:29], v[172:175], v[212:215], v[26:29]
	v_mfma_f32_16x16x32_bf16 v[18:21], v[164:167], v[220:223], v[18:21]
	v_mfma_f32_16x16x32_bf16 v[10:13], v[172:175], v[220:223], v[10:13]
	v_mfma_f32_16x16x32_bf16 v[54:57], v[176:179], v[192:195], 0
	v_mfma_f32_16x16x32_bf16 v[46:49], v[184:187], v[192:195], 0
	v_mfma_f32_16x16x32_bf16 v[38:41], v[176:179], v[200:203], 0
	v_mfma_f32_16x16x32_bf16 v[30:33], v[184:187], v[200:203], 0
	v_mfma_f32_16x16x32_bf16 v[22:25], v[176:179], v[208:211], 0
	v_mfma_f32_16x16x32_bf16 v[14:17], v[184:187], v[208:211], 0
	v_mfma_f32_16x16x32_bf16 v[6:9], v[176:179], v[216:219], 0
	v_mfma_f32_16x16x32_bf16 v[2:5], v[184:187], v[216:219], 0
	v_mfma_f32_16x16x32_bf16 v[54:57], v[180:183], v[196:199], v[54:57]
	v_mfma_f32_16x16x32_bf16 v[46:49], v[188:191], v[196:199], v[46:49]
	v_mfma_f32_16x16x32_bf16 v[38:41], v[180:183], v[204:207], v[38:41]
	v_mfma_f32_16x16x32_bf16 v[30:33], v[188:191], v[204:207], v[30:33]
	v_mfma_f32_16x16x32_bf16 v[22:25], v[180:183], v[212:215], v[22:25]
	v_mfma_f32_16x16x32_bf16 v[14:17], v[188:191], v[212:215], v[14:17]
	v_mfma_f32_16x16x32_bf16 v[6:9], v[180:183], v[220:223], v[6:9]
	v_mfma_f32_16x16x32_bf16 v[2:5], v[188:191], v[220:223], v[2:5]
	s_setprio 0
	s_barrier
	s_add_i32 s69, 0, 0x18000
	v_add_u32_e32 v155, s69, v1
	s_add_i32 s70, 0, 0x1c000
	ds_read_b128 v[156:159], v155
	ds_read_b128 v[164:167], v155 offset:1024
	ds_read_b128 v[168:171], v155 offset:2048
	ds_read_b128 v[172:175], v155 offset:3072
	v_add_u32_e32 v155, s70, v1
	ds_read_b128 v[176:179], v155
	ds_read_b128 v[180:183], v155 offset:1024
	ds_read_b128 v[184:187], v155 offset:2048
	ds_read_b128 v[188:191], v155 offset:3072
	s_add_u32 s40, s40, 0x40000
	s_addc_u32 s41, s41, 0
	s_mov_b32 m0, s47
	v_lshl_add_u64 v[228:229], s[40:41], 0, v[130:131]
	ds_read_b128 v[192:195], v154 offset:32768
	ds_read_b128 v[196:199], v154 offset:33792
	ds_read_b128 v[200:203], v154 offset:34816
	ds_read_b128 v[204:207], v154 offset:35840
	ds_read_b128 v[208:211], v154 offset:36864
	ds_read_b128 v[212:215], v154 offset:37888
	ds_read_b128 v[216:219], v154 offset:38912
	ds_read_b128 v[220:223], v154 offset:39936
	global_load_lds_dwordx4 v[228:229], off
	s_mov_b32 m0, s48
	v_lshl_add_u64 v[228:229], s[40:41], 0, v[134:135]
	global_load_lds_dwordx4 v[228:229], off
	s_waitcnt vmcnt(8)
	s_waitcnt lgkmcnt(0)
	s_barrier
	s_setprio 1
	s_waitcnt lgkmcnt(0)
	v_mfma_f32_16x16x32_bf16 v[126:129], v[156:159], v[192:195], v[126:129]
	v_mfma_f32_16x16x32_bf16 v[122:125], v[168:171], v[192:195], v[122:125]
	v_mfma_f32_16x16x32_bf16 v[114:117], v[156:159], v[200:203], v[114:117]
	v_mfma_f32_16x16x32_bf16 v[106:109], v[168:171], v[200:203], v[106:109]
	v_mfma_f32_16x16x32_bf16 v[98:101], v[156:159], v[208:211], v[98:101]
	v_mfma_f32_16x16x32_bf16 v[90:93], v[168:171], v[208:211], v[90:93]
	v_mfma_f32_16x16x32_bf16 v[82:85], v[156:159], v[216:219], v[82:85]
	v_mfma_f32_16x16x32_bf16 v[74:77], v[168:171], v[216:219], v[74:77]
	v_mfma_f32_16x16x32_bf16 v[126:129], v[164:167], v[196:199], v[126:129]
	v_mfma_f32_16x16x32_bf16 v[122:125], v[172:175], v[196:199], v[122:125]
	v_mfma_f32_16x16x32_bf16 v[114:117], v[164:167], v[204:207], v[114:117]
	v_mfma_f32_16x16x32_bf16 v[106:109], v[172:175], v[204:207], v[106:109]
	v_mfma_f32_16x16x32_bf16 v[98:101], v[164:167], v[212:215], v[98:101]
	v_mfma_f32_16x16x32_bf16 v[90:93], v[172:175], v[212:215], v[90:93]
	v_mfma_f32_16x16x32_bf16 v[82:85], v[164:167], v[220:223], v[82:85]
	v_mfma_f32_16x16x32_bf16 v[74:77], v[172:175], v[220:223], v[74:77]
	v_mfma_f32_16x16x32_bf16 v[118:121], v[176:179], v[192:195], v[118:121]
	v_mfma_f32_16x16x32_bf16 v[110:113], v[184:187], v[192:195], v[110:113]
	v_mfma_f32_16x16x32_bf16 v[102:105], v[176:179], v[200:203], v[102:105]
	v_mfma_f32_16x16x32_bf16 v[94:97], v[184:187], v[200:203], v[94:97]
	v_mfma_f32_16x16x32_bf16 v[86:89], v[176:179], v[208:211], v[86:89]
	v_mfma_f32_16x16x32_bf16 v[78:81], v[184:187], v[208:211], v[78:81]
	v_mfma_f32_16x16x32_bf16 v[70:73], v[176:179], v[216:219], v[70:73]
	v_mfma_f32_16x16x32_bf16 v[66:69], v[184:187], v[216:219], v[66:69]
	v_mfma_f32_16x16x32_bf16 v[118:121], v[180:183], v[196:199], v[118:121]
	v_mfma_f32_16x16x32_bf16 v[110:113], v[188:191], v[196:199], v[110:113]
	v_mfma_f32_16x16x32_bf16 v[102:105], v[180:183], v[204:207], v[102:105]
	v_mfma_f32_16x16x32_bf16 v[94:97], v[188:191], v[204:207], v[94:97]
	v_mfma_f32_16x16x32_bf16 v[86:89], v[180:183], v[212:215], v[86:89]
	v_mfma_f32_16x16x32_bf16 v[78:81], v[188:191], v[212:215], v[78:81]
	v_mfma_f32_16x16x32_bf16 v[70:73], v[180:183], v[220:223], v[70:73]
	v_mfma_f32_16x16x32_bf16 v[66:69], v[188:191], v[220:223], v[66:69]
	s_setprio 0
	s_barrier
; #define PG8_STAGE(bufoff, gbase, voff) do { _Pragma("unroll") for (int _i = 0; _i < 2; ++_i) \
;         __builtin_amdgcn_global_load_lds((const unsigned*)((const char*)(gbase) + (voff)[_i]), (PG8_LAS unsigned*)(lds + (bufoff) + ldsw + _i * 8192), 16, 0, 0); } while (0)
; #define PG8_LDA(dst, b, h) do { _Pragma("unroll") for (int m = 0; m < 4; ++m) _Pragma("unroll") for (int k = 0; k < 2; ++k) dst[m][k] = *(const PG8_LAS bf16x8*)(lds + PG8_SA(b, h) + aoff + m * 2048 + k * 1024); } while (0)
; #define PG8_MMA(ai, bj, At, Bt) do { __builtin_amdgcn_s_setprio(1); _Pragma("unroll") for (int m = 0; m < 4; ++m) _Pragma("unroll") for (int n = 0; n < 2; ++n) _Pragma("unroll") for (int k = 0; k < 2; ++k) \
;         acc[ai][bj][m][n] = __builtin_amdgcn_mfma_f32_16x16x32_bf16(Bt[n][k], At[m][k], acc[ai][bj][m][n], 0, 0, 0); __builtin_amdgcn_s_setprio(0); } while (0)
; #define PG8_WAIT_V(n) asm volatile("s_waitcnt vmcnt(" #n ")" ::: "memory")
; #define PG8_WAIT_L(n) asm volatile("s_waitcnt lgkmcnt(" #n ")" ::: "memory")
; #define PG8_BAR __builtin_amdgcn_s_barrier()
; #define PG8_SCHED __builtin_amdgcn_sched_barrier(0)
; template <class Epi, class Sched, bool ALIGN_EPI = true>
; __device__ __forceinline__ void gemm_phase(PG8_LAS unsigned char* lds, const int K, const Sched& S, const Epi& E) {
;     ...
;             PG8_LDA(At, 1, 1); PG8_STAGE(PG8_SB(1, 0), b3, voffB); PG8_STAGE(PG8_SB(1, 1), b3 + hstep, voffB); PG8_STAGE(PG8_SA(1, 0), a3, voffA);
;             PG8_WAIT_V(8); PG8_WAIT_L(0); PG8_BAR; PG8_MMA(1, 0, At, B0); PG8_MMA(1, 1, At, B1); PG8_BAR; PG8_SCHED;
;         }
	s_add_i32 s40, s69, s44
	v_lshl_add_u64 v[150:151], v[150:151], 0, s[10:11]
	s_mov_b32 m0, s40
	ds_read_b128 v[192:195], v154 offset:49152
	ds_read_b128 v[196:199], v154 offset:50176
	ds_read_b128 v[200:203], v154 offset:51200
	ds_read_b128 v[204:207], v154 offset:52224
	ds_read_b128 v[208:211], v154 offset:53248
	ds_read_b128 v[212:215], v154 offset:54272
	ds_read_b128 v[216:219], v154 offset:55296
	ds_read_b128 v[220:223], v154 offset:56320
	global_load_lds_dwordx4 v[150:151], off
	s_add_i32 m0, s40, 0x2000
	s_add_u32 s38, s38, 0x40080
	v_lshl_add_u64 v[150:151], v[160:161], 0, s[10:11]
	s_addc_u32 s39, s39, 0
	s_add_i32 s40, s70, s44
	global_load_lds_dwordx4 v[150:151], off
	s_mov_b32 m0, s40
	v_lshl_add_u64 v[150:151], s[38:39], 0, v[132:133]
	global_load_lds_dwordx4 v[150:151], off
	s_add_i32 m0, s40, 0x2000
	v_lshl_add_u64 v[150:151], s[38:39], 0, v[136:137]
	global_load_lds_dwordx4 v[150:151], off
	s_mov_b32 m0, s49
	v_lshl_add_u64 v[150:151], v[224:225], 0, s[10:11]
	global_load_lds_dwordx4 v[150:151], off
	s_mov_b32 m0, s50
	v_lshl_add_u64 v[150:151], v[226:227], 0, s[10:11]
	global_load_lds_dwordx4 v[150:151], off
	s_waitcnt vmcnt(8)
	s_waitcnt lgkmcnt(0)
	s_barrier
	s_setprio 1
	s_waitcnt lgkmcnt(0)
	v_mfma_f32_16x16x32_bf16 v[62:65], v[156:159], v[192:195], v[62:65]
	v_mfma_f32_16x16x32_bf16 v[58:61], v[168:171], v[192:195], v[58:61]
	v_mfma_f32_16x16x32_bf16 v[50:53], v[156:159], v[200:203], v[50:53]
	v_mfma_f32_16x16x32_bf16 v[42:45], v[168:171], v[200:203], v[42:45]
	v_mfma_f32_16x16x32_bf16 v[34:37], v[156:159], v[208:211], v[34:37]
	v_mfma_f32_16x16x32_bf16 v[26:29], v[168:171], v[208:211], v[26:29]
	v_mfma_f32_16x16x32_bf16 v[18:21], v[156:159], v[216:219], v[18:21]
	v_mfma_f32_16x16x32_bf16 v[10:13], v[168:171], v[216:219], v[10:13]
	v_mfma_f32_16x16x32_bf16 v[62:65], v[164:167], v[196:199], v[62:65]
	v_mfma_f32_16x16x32_bf16 v[58:61], v[172:175], v[196:199], v[58:61]
	v_mfma_f32_16x16x32_bf16 v[50:53], v[164:167], v[204:207], v[50:53]
	v_mfma_f32_16x16x32_bf16 v[42:45], v[172:175], v[204:207], v[42:45]
	v_mfma_f32_16x16x32_bf16 v[34:37], v[164:167], v[212:215], v[34:37]
	v_mfma_f32_16x16x32_bf16 v[26:29], v[172:175], v[212:215], v[26:29]
	v_mfma_f32_16x16x32_bf16 v[18:21], v[164:167], v[220:223], v[18:21]
	v_mfma_f32_16x16x32_bf16 v[10:13], v[172:175], v[220:223], v[10:13]
	v_mfma_f32_16x16x32_bf16 v[54:57], v[176:179], v[192:195], v[54:57]
	v_mfma_f32_16x16x32_bf16 v[46:49], v[184:187], v[192:195], v[46:49]
	v_mfma_f32_16x16x32_bf16 v[38:41], v[176:179], v[200:203], v[38:41]
	v_mfma_f32_16x16x32_bf16 v[30:33], v[184:187], v[200:203], v[30:33]
	v_mfma_f32_16x16x32_bf16 v[22:25], v[176:179], v[208:211], v[22:25]
	v_mfma_f32_16x16x32_bf16 v[14:17], v[184:187], v[208:211], v[14:17]
	v_mfma_f32_16x16x32_bf16 v[6:9], v[176:179], v[216:219], v[6:9]
	v_mfma_f32_16x16x32_bf16 v[2:5], v[184:187], v[216:219], v[2:5]
	v_mfma_f32_16x16x32_bf16 v[54:57], v[180:183], v[196:199], v[54:57]
	v_mfma_f32_16x16x32_bf16 v[46:49], v[188:191], v[196:199], v[46:49]
	v_mfma_f32_16x16x32_bf16 v[38:41], v[180:183], v[204:207], v[38:41]
	v_mfma_f32_16x16x32_bf16 v[30:33], v[188:191], v[204:207], v[30:33]
	v_mfma_f32_16x16x32_bf16 v[22:25], v[180:183], v[212:215], v[22:25]
	v_mfma_f32_16x16x32_bf16 v[14:17], v[188:191], v[212:215], v[14:17]
	v_mfma_f32_16x16x32_bf16 v[6:9], v[180:183], v[220:223], v[6:9]
	v_mfma_f32_16x16x32_bf16 v[2:5], v[188:191], v[220:223], v[2:5]
	s_setprio 0
	s_barrier
	s_add_i32 s68, s68, 2
	s_add_u32 s36, s36, 0x100
	s_addc_u32 s37, s37, 0
	s_add_u32 s66, s66, 0x100
	s_addc_u32 s67, s67, 0
	s_cmp_gt_u32 s68, 13
	s_cbranch_scc0 .LBB0_1713
	s_branch .Lkexit_3

; #define PG8_BAR __builtin_amdgcn_s_barrier()
; template <class Epi, class Sched, bool ALIGN_EPI = true>
; __device__ __forceinline__ void gemm_phase(PG8_LAS unsigned char* lds, const int K, const Sched& S, const Epi& E) {
;     ...
;         if constexpr (ALIGN_EPI) { if (wr == 0) PG8_BAR; }
.Lkexit_3:
	s_and_b64 vcc, exec, s[12:13]
	s_cbranch_vccz .LBB0_1716
	s_barrier

; #define PG8_STAGE(bufoff, gbase, voff) do { _Pragma("unroll") for (int _i = 0; _i < 2; ++_i) \
;         __builtin_amdgcn_global_load_lds((const unsigned*)((const char*)(gbase) + (voff)[_i]), (PG8_LAS unsigned*)(lds + (bufoff) + ldsw + _i * 8192), 16, 0, 0); } while (0)
; #define PG8_LDA(dst, b, h) do { _Pragma("unroll") for (int m = 0; m < 4; ++m) _Pragma("unroll") for (int k = 0; k < 2; ++k) dst[m][k] = *(const PG8_LAS bf16x8*)(lds + PG8_SA(b, h) + aoff + m * 2048 + k * 1024); } while (0)
; #define PG8_LDB(dst, b, h) do { _Pragma("unroll") for (int n = 0; n < 2; ++n) _Pragma("unroll") for (int k = 0; k < 2; ++k) dst[n][k] = *(const PG8_LAS bf16x8*)(lds + PG8_SB(b, h) + boff + n * 2048 + k * 1024); } while (0)
; #define PG8_MMA(ai, bj, At, Bt) do { __builtin_amdgcn_s_setprio(1); _Pragma("unroll") for (int m = 0; m < 4; ++m) _Pragma("unroll") for (int n = 0; n < 2; ++n) _Pragma("unroll") for (int k = 0; k < 2; ++k) \
;         acc[ai][bj][m][n] = __builtin_amdgcn_mfma_f32_16x16x32_bf16(Bt[n][k], At[m][k], acc[ai][bj][m][n], 0, 0, 0); __builtin_amdgcn_s_setprio(0); } while (0)
; #define PG8_BAR __builtin_amdgcn_s_barrier()
; template <class Epi, class Sched, bool ALIGN_EPI = true>
; __device__ __forceinline__ void gemm_phase(PG8_LAS unsigned char* lds, const int K, const Sched& S, const Epi& E) {
;     ...
;         const char* nA = has_next ? S.aptr(nxt) : cA; const char* nB = has_next ? S.bptr(nxt) : cB;
;         unsigned td = 0u;
;         if constexpr (Epi::TOUCH) E.touch(cur, tid, td);
;         for (int t = 0; t < nt; t += 2) {
;             const bool last = (t == nt - 2);
;             const char* a1 = cA + (size_t)(t + 1) * kstep;
;             const char* a2 = last ? nA : cA + (size_t)(t + 2) * kstep; const char* b2 = last ? nB : cB + (size_t)(t + 2) * kstep;
;             const char* a3 = a2 + kstep; const char* b3 = b2 + kstep;
;             PG8_LDB(B0, 0, 0); PG8_LDB(B1, 0, 1); PG8_SCHED; PG8_LDA(At, 0, 0); PG8_STAGE(PG8_SA(1, 1), a1 + hstep, voffA);
;             PG8_WAIT_V(8); PG8_WAIT_L(0); PG8_BAR; PG8_MMA(0, 0, At, B0); PG8_MMA(0, 1, At, B1); PG8_BAR; PG8_SCHED;
;             PG8_LDA(At, 0, 1); PG8_STAGE(PG8_SB(0, 0), b2, voffB); PG8_STAGE(PG8_SB(0, 1), b2 + hstep, voffB); PG8_STAGE(PG8_SA(0, 0), a2, voffA);
;             PG8_WAIT_V(8); PG8_WAIT_L(0); PG8_BAR; PG8_MMA(1, 0, At, B0); PG8_MMA(1, 1, At, B1); PG8_BAR; PG8_SCHED;
.LBB0_1813:
	s_ashr_i32 s43, s42, 31
	s_lshl_b64 s[44:45], s[42:43], 21
	s_add_u32 s44, s35, s44
	s_addc_u32 s45, s39, s45
	s_and_b64 s[48:49], s[46:47], exec
	s_cselect_b32 s11, s45, s55
	s_cselect_b32 s43, s44, s54
	s_ashr_i32 s41, s40, 31
	s_lshl_b64 s[48:49], s[40:41], 21
	s_add_u32 s48, s60, s48
	s_addc_u32 s49, s61, s49
	s_and_b64 s[58:59], s[46:47], exec
	s_cselect_b32 s41, s49, s57
	s_cselect_b32 s51, s48, s56
	s_add_u32 s54, s54, 0x100080
	s_addc_u32 s55, s55, 0
	s_add_u32 s91, s56, 0x100
	s_addc_u32 s92, s57, 0
	s_mov_b32 s93, -2
	ds_read_b128 v[128:131], v179
	ds_read_b128 v[132:135], v179 offset:1024
	ds_read_b128 v[136:139], v179 offset:2048
	ds_read_b128 v[140:143], v179 offset:3072
	ds_read_b128 v[144:147], v180
	ds_read_b128 v[162:165], v180 offset:1024
	ds_read_b128 v[166:169], v180 offset:2048
	ds_read_b128 v[170:173], v180 offset:3072
	s_add_u32 s56, s54, 0xfff00080
	s_addc_u32 s57, s55, -1
	s_cmp_eq_u32 s93, 60
	s_cselect_b32 s59, s11, s57
	s_cselect_b32 s58, s43, s56
	s_cselect_b32 s57, s41, s92
	s_cselect_b32 s56, s51, s91
	v_lshl_add_u64 v[222:223], s[54:55], 0, v[154:155]
	s_add_i32 m0, s63, 0xc000
	ds_read_b128 v[190:193], v181
	ds_read_b128 v[194:197], v181 offset:1024
	ds_read_b128 v[198:201], v181 offset:2048
	ds_read_b128 v[202:205], v181 offset:3072
	ds_read_b128 v[206:209], v181 offset:4096
	ds_read_b128 v[210:213], v181 offset:5120
	ds_read_b128 v[214:217], v181 offset:6144
	ds_read_b128 v[218:221], v181 offset:7168
	global_load_lds_dwordx4 v[222:223], off
	s_add_i32 m0, s63, 0xe000
	v_lshl_add_u64 v[222:223], s[54:55], 0, v[156:157]
	global_load_lds_dwordx4 v[222:223], off
	s_waitcnt vmcnt(8)
	s_waitcnt lgkmcnt(0)
	s_barrier
	s_setprio 1
	s_waitcnt lgkmcnt(0)
	v_mfma_f32_16x16x32_bf16 v[56:59], v[128:131], v[190:193], 0
	v_mfma_f32_16x16x32_bf16 v[32:35], v[136:139], v[190:193], 0
	v_mfma_f32_16x16x32_bf16 v[72:75], v[128:131], v[198:201], 0
	v_mfma_f32_16x16x32_bf16 v[44:47], v[136:139], v[198:201], 0
	v_mfma_f32_16x16x32_bf16 v[84:87], v[128:131], v[206:209], 0
	v_mfma_f32_16x16x32_bf16 v[52:55], v[136:139], v[206:209], 0
	v_mfma_f32_16x16x32_bf16 v[108:111], v[128:131], v[214:217], 0
	v_mfma_f32_16x16x32_bf16 v[64:67], v[136:139], v[214:217], 0
	v_mfma_f32_16x16x32_bf16 v[56:59], v[132:135], v[194:197], v[56:59]
	v_mfma_f32_16x16x32_bf16 v[32:35], v[140:143], v[194:197], v[32:35]
	v_mfma_f32_16x16x32_bf16 v[72:75], v[132:135], v[202:205], v[72:75]
	v_mfma_f32_16x16x32_bf16 v[44:47], v[140:143], v[202:205], v[44:47]
	v_mfma_f32_16x16x32_bf16 v[84:87], v[132:135], v[210:213], v[84:87]
	v_mfma_f32_16x16x32_bf16 v[52:55], v[140:143], v[210:213], v[52:55]
	v_mfma_f32_16x16x32_bf16 v[108:111], v[132:135], v[218:221], v[108:111]
	v_mfma_f32_16x16x32_bf16 v[64:67], v[140:143], v[218:221], v[64:67]
	v_mfma_f32_16x16x32_bf16 v[12:15], v[144:147], v[190:193], 0
	v_mfma_f32_16x16x32_bf16 v[0:3], v[166:169], v[190:193], 0
	v_mfma_f32_16x16x32_bf16 v[20:23], v[144:147], v[198:201], 0
	v_mfma_f32_16x16x32_bf16 v[4:7], v[166:169], v[198:201], 0
	v_mfma_f32_16x16x32_bf16 v[28:31], v[144:147], v[206:209], 0
	v_mfma_f32_16x16x32_bf16 v[8:11], v[166:169], v[206:209], 0
	v_mfma_f32_16x16x32_bf16 v[40:43], v[144:147], v[214:217], 0
	v_mfma_f32_16x16x32_bf16 v[16:19], v[166:169], v[214:217], 0
	v_mfma_f32_16x16x32_bf16 v[12:15], v[162:165], v[194:197], v[12:15]
	v_mfma_f32_16x16x32_bf16 v[0:3], v[170:173], v[194:197], v[0:3]
	v_mfma_f32_16x16x32_bf16 v[20:23], v[162:165], v[202:205], v[20:23]
	v_mfma_f32_16x16x32_bf16 v[4:7], v[170:173], v[202:205], v[4:7]
	v_mfma_f32_16x16x32_bf16 v[28:31], v[162:165], v[210:213], v[28:31]
	v_mfma_f32_16x16x32_bf16 v[8:11], v[170:173], v[210:213], v[8:11]
	v_mfma_f32_16x16x32_bf16 v[40:43], v[162:165], v[218:221], v[40:43]
	v_mfma_f32_16x16x32_bf16 v[16:19], v[170:173], v[218:221], v[16:19]
	s_setprio 0
	s_barrier
	s_add_i32 s94, s76, s62
	v_lshl_add_u64 v[222:223], s[56:57], 0, v[148:149]
	s_mov_b32 m0, s94
	ds_read_b128 v[190:193], v181 offset:16384
	ds_read_b128 v[194:197], v181 offset:17408
	ds_read_b128 v[198:201], v181 offset:18432
	ds_read_b128 v[202:205], v181 offset:19456
	ds_read_b128 v[206:209], v181 offset:20480
	ds_read_b128 v[210:213], v181 offset:21504
	ds_read_b128 v[214:217], v181 offset:22528
	ds_read_b128 v[218:221], v181 offset:23552
	global_load_lds_dwordx4 v[222:223], off
	s_add_i32 m0, s94, 0x2000
	s_add_u32 s94, s56, 0x100000
	v_lshl_add_u64 v[224:225], s[56:57], 0, v[150:151]
	s_addc_u32 s95, s57, 0
	s_add_i32 s96, s77, s62
	global_load_lds_dwordx4 v[224:225], off
	v_lshl_add_u64 v[226:227], s[94:95], 0, v[148:149]
	s_mov_b32 m0, s96
	v_lshl_add_u64 v[228:229], s[58:59], 0, v[150:151]
	global_load_lds_dwordx4 v[226:227], off
	s_add_i32 m0, s96, 0x2000
	v_lshl_add_u64 v[226:227], s[94:95], 0, v[150:151]
	global_load_lds_dwordx4 v[226:227], off
	s_mov_b32 m0, s63
	v_lshl_add_u64 v[226:227], s[58:59], 0, v[148:149]
	global_load_lds_dwordx4 v[226:227], off
	s_mov_b32 m0, s64
	s_nop 0
	global_load_lds_dwordx4 v[228:229], off
	s_waitcnt vmcnt(8)
	s_waitcnt lgkmcnt(0)
	s_barrier
; #define PG8_STAGE(bufoff, gbase, voff) do { _Pragma("unroll") for (int _i = 0; _i < 2; ++_i) \
;         __builtin_amdgcn_global_load_lds((const unsigned*)((const char*)(gbase) + (voff)[_i]), (PG8_LAS unsigned*)(lds + (bufoff) + ldsw + _i * 8192), 16, 0, 0); } while (0)
; #define PG8_LDA(dst, b, h) do { _Pragma("unroll") for (int m = 0; m < 4; ++m) _Pragma("unroll") for (int k = 0; k < 2; ++k) dst[m][k] = *(const PG8_LAS bf16x8*)(lds + PG8_SA(b, h) + aoff + m * 2048 + k * 1024); } while (0)
; #define PG8_LDB(dst, b, h) do { _Pragma("unroll") for (int n = 0; n < 2; ++n) _Pragma("unroll") for (int k = 0; k < 2; ++k) dst[n][k] = *(const PG8_LAS bf16x8*)(lds + PG8_SB(b, h) + boff + n * 2048 + k * 1024); } while (0)
; #define PG8_MMA(ai, bj, At, Bt) do { __builtin_amdgcn_s_setprio(1); _Pragma("unroll") for (int m = 0; m < 4; ++m) _Pragma("unroll") for (int n = 0; n < 2; ++n) _Pragma("unroll") for (int k = 0; k < 2; ++k) \
;         acc[ai][bj][m][n] = __builtin_amdgcn_mfma_f32_16x16x32_bf16(Bt[n][k], At[m][k], acc[ai][bj][m][n], 0, 0, 0); __builtin_amdgcn_s_setprio(0); } while (0)
; #define PG8_WAIT_V(n) asm volatile("s_waitcnt vmcnt(" #n ")" ::: "memory")
; #define PG8_WAIT_L(n) asm volatile("s_waitcnt lgkmcnt(" #n ")" ::: "memory")
; #define PG8_BAR __builtin_amdgcn_s_barrier()
; #define PG8_SCHED __builtin_amdgcn_sched_barrier(0)
; template <class Epi, class Sched, bool ALIGN_EPI = true>
; __device__ __forceinline__ void gemm_phase(PG8_LAS unsigned char* lds, const int K, const Sched& S, const Epi& E) {
;     ...
;             PG8_WAIT_V(8); PG8_WAIT_L(0); PG8_BAR; PG8_MMA(0, 0, At, B0); PG8_MMA(0, 1, At, B1); PG8_BAR; PG8_SCHED;
;             PG8_LDA(At, 0, 1); PG8_STAGE(PG8_SB(0, 0), b2, voffB); PG8_STAGE(PG8_SB(0, 1), b2 + hstep, voffB); PG8_STAGE(PG8_SA(0, 0), a2, voffA);
;             PG8_WAIT_V(8); PG8_WAIT_L(0); PG8_BAR; PG8_MMA(1, 0, At, B0); PG8_MMA(1, 1, At, B1); PG8_BAR; PG8_SCHED;
;             PG8_LDB(B0, 1, 0); PG8_LDB(B1, 1, 1); PG8_SCHED; PG8_LDA(At, 1, 0); PG8_STAGE(PG8_SA(0, 1), a2 + hstep, voffA);
;             PG8_WAIT_V(8); PG8_WAIT_L(0); PG8_BAR; PG8_MMA(0, 0, At, B0); PG8_MMA(0, 1, At, B1); PG8_BAR; PG8_SCHED;
	s_setprio 1
	s_waitcnt lgkmcnt(0)
	v_mfma_f32_16x16x32_bf16 v[112:115], v[128:131], v[190:193], 0
	v_mfma_f32_16x16x32_bf16 v[76:79], v[136:139], v[190:193], 0
	v_mfma_f32_16x16x32_bf16 v[124:127], v[128:131], v[198:201], 0
	v_mfma_f32_16x16x32_bf16 v[88:91], v[136:139], v[198:201], 0
	v_mfma_f32_16x16x32_bf16 v[120:123], v[128:131], v[206:209], 0
	v_mfma_f32_16x16x32_bf16 v[116:119], v[136:139], v[206:209], 0
	v_mfma_f32_16x16x32_bf16 v[104:107], v[128:131], v[214:217], 0
	v_mfma_f32_16x16x32_bf16 v[100:103], v[136:139], v[214:217], 0
	v_mfma_f32_16x16x32_bf16 v[112:115], v[132:135], v[194:197], v[112:115]
	v_mfma_f32_16x16x32_bf16 v[76:79], v[140:143], v[194:197], v[76:79]
	v_mfma_f32_16x16x32_bf16 v[124:127], v[132:135], v[202:205], v[124:127]
	v_mfma_f32_16x16x32_bf16 v[88:91], v[140:143], v[202:205], v[88:91]
	v_mfma_f32_16x16x32_bf16 v[120:123], v[132:135], v[210:213], v[120:123]
	v_mfma_f32_16x16x32_bf16 v[116:119], v[140:143], v[210:213], v[116:119]
	v_mfma_f32_16x16x32_bf16 v[104:107], v[132:135], v[218:221], v[104:107]
	v_mfma_f32_16x16x32_bf16 v[100:103], v[140:143], v[218:221], v[100:103]
	v_mfma_f32_16x16x32_bf16 v[48:51], v[144:147], v[190:193], 0
	v_mfma_f32_16x16x32_bf16 v[24:27], v[166:169], v[190:193], 0
	v_mfma_f32_16x16x32_bf16 v[60:63], v[144:147], v[198:201], 0
	v_mfma_f32_16x16x32_bf16 v[36:39], v[166:169], v[198:201], 0
	v_mfma_f32_16x16x32_bf16 v[96:99], v[144:147], v[206:209], 0
	v_mfma_f32_16x16x32_bf16 v[68:71], v[166:169], v[206:209], 0
	v_mfma_f32_16x16x32_bf16 v[92:95], v[144:147], v[214:217], 0
	v_mfma_f32_16x16x32_bf16 v[80:83], v[166:169], v[214:217], 0
	v_mfma_f32_16x16x32_bf16 v[48:51], v[162:165], v[194:197], v[48:51]
	v_mfma_f32_16x16x32_bf16 v[24:27], v[170:173], v[194:197], v[24:27]
	v_mfma_f32_16x16x32_bf16 v[60:63], v[162:165], v[202:205], v[60:63]
	v_mfma_f32_16x16x32_bf16 v[36:39], v[170:173], v[202:205], v[36:39]
	v_mfma_f32_16x16x32_bf16 v[96:99], v[162:165], v[210:213], v[96:99]
	v_mfma_f32_16x16x32_bf16 v[68:71], v[170:173], v[210:213], v[68:71]
	v_mfma_f32_16x16x32_bf16 v[92:95], v[162:165], v[218:221], v[92:95]
	v_mfma_f32_16x16x32_bf16 v[80:83], v[170:173], v[218:221], v[80:83]
	s_setprio 0
	s_barrier
	s_add_i32 s94, 0, 0x18000
	s_add_i32 s95, 0, 0x1c000
	v_add_u32_e32 v140, s94, v174
	v_add_u32_e32 v170, s95, v174
	ds_read_b128 v[128:131], v140
	ds_read_b128 v[132:135], v140 offset:1024
	ds_read_b128 v[136:139], v140 offset:2048
	ds_read_b128 v[140:143], v140 offset:3072
	ds_read_b128 v[144:147], v170
	ds_read_b128 v[162:165], v170 offset:1024
	ds_read_b128 v[166:169], v170 offset:2048
	ds_read_b128 v[170:173], v170 offset:3072
	s_add_u32 s58, s58, 0x100000
	s_addc_u32 s59, s59, 0
	s_mov_b32 m0, s65
	v_lshl_add_u64 v[230:231], s[58:59], 0, v[148:149]
	ds_read_b128 v[190:193], v181 offset:32768
	ds_read_b128 v[194:197], v181 offset:33792
	ds_read_b128 v[198:201], v181 offset:34816
	ds_read_b128 v[202:205], v181 offset:35840
	ds_read_b128 v[206:209], v181 offset:36864
	ds_read_b128 v[210:213], v181 offset:37888
	ds_read_b128 v[214:217], v181 offset:38912
	ds_read_b128 v[218:221], v181 offset:39936
	global_load_lds_dwordx4 v[230:231], off
	s_mov_b32 m0, s66
	v_lshl_add_u64 v[230:231], s[58:59], 0, v[150:151]
	global_load_lds_dwordx4 v[230:231], off
	s_waitcnt vmcnt(8)
	s_waitcnt lgkmcnt(0)
	s_barrier
	s_setprio 1
	s_waitcnt lgkmcnt(0)
	v_mfma_f32_16x16x32_bf16 v[56:59], v[128:131], v[190:193], v[56:59]
	v_mfma_f32_16x16x32_bf16 v[32:35], v[136:139], v[190:193], v[32:35]
	v_mfma_f32_16x16x32_bf16 v[72:75], v[128:131], v[198:201], v[72:75]
	v_mfma_f32_16x16x32_bf16 v[44:47], v[136:139], v[198:201], v[44:47]
	v_mfma_f32_16x16x32_bf16 v[84:87], v[128:131], v[206:209], v[84:87]
	v_mfma_f32_16x16x32_bf16 v[52:55], v[136:139], v[206:209], v[52:55]
	v_mfma_f32_16x16x32_bf16 v[108:111], v[128:131], v[214:217], v[108:111]
	v_mfma_f32_16x16x32_bf16 v[64:67], v[136:139], v[214:217], v[64:67]
	v_mfma_f32_16x16x32_bf16 v[56:59], v[132:135], v[194:197], v[56:59]
	v_mfma_f32_16x16x32_bf16 v[32:35], v[140:143], v[194:197], v[32:35]
	v_mfma_f32_16x16x32_bf16 v[72:75], v[132:135], v[202:205], v[72:75]
	v_mfma_f32_16x16x32_bf16 v[44:47], v[140:143], v[202:205], v[44:47]
	v_mfma_f32_16x16x32_bf16 v[84:87], v[132:135], v[210:213], v[84:87]
	v_mfma_f32_16x16x32_bf16 v[52:55], v[140:143], v[210:213], v[52:55]
	v_mfma_f32_16x16x32_bf16 v[108:111], v[132:135], v[218:221], v[108:111]
	v_mfma_f32_16x16x32_bf16 v[64:67], v[140:143], v[218:221], v[64:67]
	v_mfma_f32_16x16x32_bf16 v[12:15], v[144:147], v[190:193], v[12:15]
	v_mfma_f32_16x16x32_bf16 v[0:3], v[166:169], v[190:193], v[0:3]
	v_mfma_f32_16x16x32_bf16 v[20:23], v[144:147], v[198:201], v[20:23]
	v_mfma_f32_16x16x32_bf16 v[4:7], v[166:169], v[198:201], v[4:7]
	v_mfma_f32_16x16x32_bf16 v[28:31], v[144:147], v[206:209], v[28:31]
	v_mfma_f32_16x16x32_bf16 v[8:11], v[166:169], v[206:209], v[8:11]
	v_mfma_f32_16x16x32_bf16 v[40:43], v[144:147], v[214:217], v[40:43]
	v_mfma_f32_16x16x32_bf16 v[16:19], v[166:169], v[214:217], v[16:19]
	v_mfma_f32_16x16x32_bf16 v[12:15], v[162:165], v[194:197], v[12:15]
	v_mfma_f32_16x16x32_bf16 v[0:3], v[170:173], v[194:197], v[0:3]
	v_mfma_f32_16x16x32_bf16 v[20:23], v[162:165], v[202:205], v[20:23]
	v_mfma_f32_16x16x32_bf16 v[4:7], v[170:173], v[202:205], v[4:7]
	v_mfma_f32_16x16x32_bf16 v[28:31], v[162:165], v[210:213], v[28:31]
	v_mfma_f32_16x16x32_bf16 v[8:11], v[170:173], v[210:213], v[8:11]
	v_mfma_f32_16x16x32_bf16 v[40:43], v[162:165], v[218:221], v[40:43]
	v_mfma_f32_16x16x32_bf16 v[16:19], v[170:173], v[218:221], v[16:19]
	s_setprio 0
	s_barrier
; #define PG8_STAGE(bufoff, gbase, voff) do { _Pragma("unroll") for (int _i = 0; _i < 2; ++_i) \
;         __builtin_amdgcn_global_load_lds((const unsigned*)((const char*)(gbase) + (voff)[_i]), (PG8_LAS unsigned*)(lds + (bufoff) + ldsw + _i * 8192), 16, 0, 0); } while (0)
; #define PG8_LDA(dst, b, h) do { _Pragma("unroll") for (int m = 0; m < 4; ++m) _Pragma("unroll") for (int k = 0; k < 2; ++k) dst[m][k] = *(const PG8_LAS bf16x8*)(lds + PG8_SA(b, h) + aoff + m * 2048 + k * 1024); } while (0)
; #define PG8_MMA(ai, bj, At, Bt) do { __builtin_amdgcn_s_setprio(1); _Pragma("unroll") for (int m = 0; m < 4; ++m) _Pragma("unroll") for (int n = 0; n < 2; ++n) _Pragma("unroll") for (int k = 0; k < 2; ++k) \
;         acc[ai][bj][m][n] = __builtin_amdgcn_mfma_f32_16x16x32_bf16(Bt[n][k], At[m][k], acc[ai][bj][m][n], 0, 0, 0); __builtin_amdgcn_s_setprio(0); } while (0)
; #define PG8_WAIT_V(n) asm volatile("s_waitcnt vmcnt(" #n ")" ::: "memory")
; #define PG8_WAIT_L(n) asm volatile("s_waitcnt lgkmcnt(" #n ")" ::: "memory")
; #define PG8_BAR __builtin_amdgcn_s_barrier()
; #define PG8_SCHED __builtin_amdgcn_sched_barrier(0)
; template <class Epi, class Sched, bool ALIGN_EPI = true>
; __device__ __forceinline__ void gemm_phase(PG8_LAS unsigned char* lds, const int K, const Sched& S, const Epi& E) {
;     ...
;             PG8_LDA(At, 1, 1); PG8_STAGE(PG8_SB(1, 0), b3, voffB); PG8_STAGE(PG8_SB(1, 1), b3 + hstep, voffB); PG8_STAGE(PG8_SA(1, 0), a3, voffA);
;             PG8_WAIT_V(8); PG8_WAIT_L(0); PG8_BAR; PG8_MMA(1, 0, At, B0); PG8_MMA(1, 1, At, B1); PG8_BAR; PG8_SCHED;
;         }
	s_add_i32 s58, s94, s62
	v_lshl_add_u64 v[222:223], v[222:223], 0, s[20:21]
	s_mov_b32 m0, s58
	ds_read_b128 v[190:193], v181 offset:49152
	ds_read_b128 v[194:197], v181 offset:50176
	ds_read_b128 v[198:201], v181 offset:51200
	ds_read_b128 v[202:205], v181 offset:52224
	ds_read_b128 v[206:209], v181 offset:53248
	ds_read_b128 v[210:213], v181 offset:54272
	ds_read_b128 v[214:217], v181 offset:55296
	ds_read_b128 v[218:221], v181 offset:56320
	global_load_lds_dwordx4 v[222:223], off
	s_add_i32 m0, s58, 0x2000
	s_add_u32 s56, s56, 0x100080
	v_lshl_add_u64 v[222:223], v[224:225], 0, s[20:21]
	s_addc_u32 s57, s57, 0
	s_add_i32 s58, s95, s62
	global_load_lds_dwordx4 v[222:223], off
	s_mov_b32 m0, s58
	v_lshl_add_u64 v[222:223], s[56:57], 0, v[148:149]
	global_load_lds_dwordx4 v[222:223], off
	s_add_i32 m0, s58, 0x2000
	v_lshl_add_u64 v[222:223], s[56:57], 0, v[150:151]
	global_load_lds_dwordx4 v[222:223], off
	s_mov_b32 m0, s70
	v_lshl_add_u64 v[222:223], v[226:227], 0, s[20:21]
	global_load_lds_dwordx4 v[222:223], off
	s_mov_b32 m0, s71
	v_lshl_add_u64 v[222:223], v[228:229], 0, s[20:21]
	global_load_lds_dwordx4 v[222:223], off
	s_waitcnt vmcnt(8)
	s_waitcnt lgkmcnt(0)
	s_barrier
	s_setprio 1
	s_waitcnt lgkmcnt(0)
	v_mfma_f32_16x16x32_bf16 v[112:115], v[128:131], v[190:193], v[112:115]
	v_mfma_f32_16x16x32_bf16 v[76:79], v[136:139], v[190:193], v[76:79]
	v_mfma_f32_16x16x32_bf16 v[124:127], v[128:131], v[198:201], v[124:127]
	v_mfma_f32_16x16x32_bf16 v[88:91], v[136:139], v[198:201], v[88:91]
	v_mfma_f32_16x16x32_bf16 v[120:123], v[128:131], v[206:209], v[120:123]
	v_mfma_f32_16x16x32_bf16 v[116:119], v[136:139], v[206:209], v[116:119]
	v_mfma_f32_16x16x32_bf16 v[104:107], v[128:131], v[214:217], v[104:107]
	v_mfma_f32_16x16x32_bf16 v[100:103], v[136:139], v[214:217], v[100:103]
	v_mfma_f32_16x16x32_bf16 v[112:115], v[132:135], v[194:197], v[112:115]
	v_mfma_f32_16x16x32_bf16 v[76:79], v[140:143], v[194:197], v[76:79]
	v_mfma_f32_16x16x32_bf16 v[124:127], v[132:135], v[202:205], v[124:127]
	v_mfma_f32_16x16x32_bf16 v[88:91], v[140:143], v[202:205], v[88:91]
	v_mfma_f32_16x16x32_bf16 v[120:123], v[132:135], v[210:213], v[120:123]
	v_mfma_f32_16x16x32_bf16 v[116:119], v[140:143], v[210:213], v[116:119]
	v_mfma_f32_16x16x32_bf16 v[104:107], v[132:135], v[218:221], v[104:107]
	v_mfma_f32_16x16x32_bf16 v[100:103], v[140:143], v[218:221], v[100:103]
	v_mfma_f32_16x16x32_bf16 v[48:51], v[144:147], v[190:193], v[48:51]
	v_mfma_f32_16x16x32_bf16 v[24:27], v[166:169], v[190:193], v[24:27]
	v_mfma_f32_16x16x32_bf16 v[60:63], v[144:147], v[198:201], v[60:63]
	v_mfma_f32_16x16x32_bf16 v[36:39], v[166:169], v[198:201], v[36:39]
	v_mfma_f32_16x16x32_bf16 v[96:99], v[144:147], v[206:209], v[96:99]
	v_mfma_f32_16x16x32_bf16 v[68:71], v[166:169], v[206:209], v[68:71]
	v_mfma_f32_16x16x32_bf16 v[92:95], v[144:147], v[214:217], v[92:95]
	v_mfma_f32_16x16x32_bf16 v[80:83], v[166:169], v[214:217], v[80:83]
	v_mfma_f32_16x16x32_bf16 v[48:51], v[162:165], v[194:197], v[48:51]
	v_mfma_f32_16x16x32_bf16 v[24:27], v[170:173], v[194:197], v[24:27]
	v_mfma_f32_16x16x32_bf16 v[60:63], v[162:165], v[202:205], v[60:63]
	v_mfma_f32_16x16x32_bf16 v[36:39], v[170:173], v[202:205], v[36:39]
	v_mfma_f32_16x16x32_bf16 v[96:99], v[162:165], v[210:213], v[96:99]
	v_mfma_f32_16x16x32_bf16 v[68:71], v[170:173], v[210:213], v[68:71]
	v_mfma_f32_16x16x32_bf16 v[92:95], v[162:165], v[218:221], v[92:95]
	v_mfma_f32_16x16x32_bf16 v[80:83], v[170:173], v[218:221], v[80:83]
	s_setprio 0
	s_barrier
	s_add_i32 s93, s93, 2
	s_add_u32 s54, s54, 0x100
	s_addc_u32 s55, s55, 0
	s_add_u32 s91, s91, 0x100
	s_addc_u32 s92, s92, 0
	s_cmp_gt_u32 s93, 61
	s_cbranch_scc0 .LBB0_1814
	s_branch .Lkexit_4

; #define PG8_BAR __builtin_amdgcn_s_barrier()
; template <class Epi, class Sched, bool ALIGN_EPI = true>
; __device__ __forceinline__ void gemm_phase(PG8_LAS unsigned char* lds, const int K, const Sched& S, const Epi& E) {
;     ...
;         if constexpr (ALIGN_EPI) { if (wr == 0) PG8_BAR; }
.Lkexit_4:
	s_and_b64 vcc, exec, s[22:23]
	s_cbranch_vccz .LBB0_1817
	s_barrier
